# write-through (sc1) on residual-stream and GLU output stores to shrink the barrier L2 writeback
# baseline (speedup 1.0000x reference)
;     __device__ __forceinline__ void operator()(const pg8::f32x4 (&acc)[2][2][4][2], const pg8::Unit& u, int wr, int wc, int fr, int fq) const {
;         const int col0 = u.pn * 256 + wc * 32 + 4 * fq;
; #pragma unroll
;         for (int ai = 0; ai < 2; ++ai)
; #pragma unroll
;             for (int m = 0; m < 4; ++m) {
;                 const int r = row_off + u.pm * 256 + ai * 128 + wr * 64 + m * 16 + fr;
;                 const bool lat = r < ML; const int bi = lat ? (r >> 13) : 4;
;                 const size_t off = lat ? (size_t)r * 1024 : (size_t)(r - ML) * 1024;
;                 const float* bp = (lat ? base_lat : base_ctx) + off + col0; float* op = (lat ? out_lat : out_ctx) + off + col0;
;                 const float* gp = gate + bi * 6144 + col0;
; #pragma unroll
;                 for (int bj = 0; bj < 2; ++bj)
; #pragma unroll
;                     for (int n = 0; n < 2; ++n) {
;                         const pg8::f32x4 g4 = *(const pg8::f32x4*)(gp + bj * 128 + n * 16), b4 = *(const pg8::f32x4*)(bp + bj * 128 + n * 16);
;                         *(pg8::f32x4*)(op + bj * 128 + n * 16) = b4 + g4 * acc[ai][bj][m][n];
;                     }
;             }
;     }
.LBB0_921:
	v_lshl_add_u32 v142, s46, 8, v136
	v_min_i32_e32 v140, 0x8000, v142
	v_cmp_gt_i32_e32 vcc, s97, v142
	v_ashrrev_i32_e32 v154, 13, v140
	v_ashrrev_i32_e32 v140, 31, v142
	v_add_u32_e32 v141, 0xffff8000, v142
	v_lshl_or_b32 v134, s47, 8, v138
	v_cndmask_b32_e32 v147, 0, v140, vcc
	v_cndmask_b32_e32 v146, v141, v142, vcc
	v_mov_b32_e32 v140, s3
	v_mov_b32_e32 v141, s53
	v_mov_b32_e32 v143, s2
	v_mov_b32_e32 v144, s52
	v_ashrrev_i32_e32 v135, 31, v134
	v_cndmask_b32_e32 v149, v140, v141, vcc
	v_cndmask_b32_e32 v148, v143, v144, vcc
	v_lshlrev_b64 v[150:151], 12, v[146:147]
	v_readlane_b32 s12, v254, 35
	v_lshl_add_u64 v[146:147], v[148:149], 0, v[150:151]
	v_lshlrev_b64 v[134:135], 2, v[134:135]
	v_readlane_b32 s13, v254, 36
	v_lshl_add_u64 v[158:159], v[146:147], 0, v[134:135]
	v_mov_b32_e32 v145, s76
	v_mov_b32_e32 v146, s13
	v_mov_b32_e32 v147, s75
	v_mov_b32_e32 v148, s12
	v_cndmask_b32_e32 v153, v145, v146, vcc
	v_cndmask_b32_e32 v152, v147, v148, vcc
	v_lshl_add_u64 v[150:151], v[152:153], 0, v[150:151]
	v_lshl_add_u64 v[160:161], v[150:151], 0, v[134:135]
	v_mul_i32_i24_e32 v150, 0x1800, v154
	v_ashrrev_i32_e32 v151, 31, v150
	v_lshl_add_u64 v[150:151], v[150:151], 2, s[6:7]
	v_lshl_add_u64 v[162:163], v[150:151], 0, v[134:135]
	global_load_dwordx4 v[164:167], v[162:163], off
	global_load_dwordx4 v[168:171], v[158:159], off
	global_load_dwordx4 v[172:175], v[162:163], off offset:64
	global_load_dwordx4 v[176:179], v[158:159], off offset:64
	global_load_dwordx4 v[180:183], v[162:163], off offset:512
	global_load_dwordx4 v[184:187], v[158:159], off offset:512
	global_load_dwordx4 v[188:191], v[162:163], off offset:576
	global_load_dwordx4 v[192:195], v[158:159], off offset:576
	s_mov_b64 s[46:47], -1
	v_readlane_b32 s79, v254, 48
	v_readlane_b32 s83, v254, 49
	s_mov_b32 s87, 0xbfc90fda
	s_brev_b32 s88, 1
	s_waitcnt vmcnt(6) lgkmcnt(0)
	v_pk_fma_f32 v[126:127], v[126:127], v[166:167], v[170:171]
	v_pk_fma_f32 v[124:125], v[124:125], v[164:165], v[168:169]
	global_store_dwordx4 v[160:161], v[124:127], off sc1
	s_waitcnt vmcnt(5) lgkmcnt(0)
	v_pk_fma_f32 v[122:123], v[122:123], v[174:175], v[178:179]
	v_pk_fma_f32 v[120:121], v[120:121], v[172:173], v[176:177]
	global_store_dwordx4 v[160:161], v[120:123], off offset:64 sc1
	s_waitcnt vmcnt(4) lgkmcnt(0)
	v_pk_fma_f32 v[118:119], v[118:119], v[182:183], v[186:187]
	v_pk_fma_f32 v[116:117], v[116:117], v[180:181], v[184:185]
	global_store_dwordx4 v[160:161], v[116:119], off offset:512 sc1
	s_waitcnt vmcnt(3) lgkmcnt(0)
	v_pk_fma_f32 v[114:115], v[114:115], v[190:191], v[194:195]
	v_pk_fma_f32 v[112:113], v[112:113], v[188:189], v[192:193]
	global_store_dwordx4 v[160:161], v[112:115], off offset:576 sc1
	s_nop 1
	v_or_b32_e32 v112, 16, v142
	v_min_i32_e32 v113, 0x8000, v112
	v_cmp_gt_i32_e32 vcc, s97, v112
	v_ashrrev_i32_e32 v116, 13, v113
	v_ashrrev_i32_e32 v113, 31, v112
	v_add_u32_e32 v114, 0xffff8010, v142
	v_cndmask_b32_e32 v113, 0, v113, vcc
	v_cndmask_b32_e32 v112, v114, v112, vcc
	v_cndmask_b32_e32 v115, v140, v141, vcc
	v_cndmask_b32_e32 v114, v143, v144, vcc
	v_lshlrev_b64 v[112:113], 12, v[112:113]
	v_lshl_add_u64 v[114:115], v[114:115], 0, v[112:113]
	v_lshl_add_u64 v[120:121], v[114:115], 0, v[134:135]
	v_cndmask_b32_e32 v115, v145, v146, vcc
	v_cndmask_b32_e32 v114, v147, v148, vcc
	v_lshl_add_u64 v[112:113], v[114:115], 0, v[112:113]
	v_lshl_add_u64 v[122:123], v[112:113], 0, v[134:135]
	v_mul_i32_i24_e32 v112, 0x1800, v116
	v_ashrrev_i32_e32 v113, 31, v112
	v_lshl_add_u64 v[112:113], v[112:113], 2, s[6:7]
	v_lshl_add_u64 v[124:125], v[112:113], 0, v[134:135]
	global_load_dwordx4 v[164:167], v[124:125], off
	global_load_dwordx4 v[168:171], v[120:121], off
	global_load_dwordx4 v[172:175], v[124:125], off offset:64
	global_load_dwordx4 v[176:179], v[120:121], off offset:64
	global_load_dwordx4 v[180:183], v[124:125], off offset:512
	global_load_dwordx4 v[184:187], v[120:121], off offset:512
	global_load_dwordx4 v[188:191], v[124:125], off offset:576
	global_load_dwordx4 v[192:195], v[120:121], off offset:576
	s_waitcnt vmcnt(6) lgkmcnt(0)
	v_pk_fma_f32 v[110:111], v[110:111], v[166:167], v[170:171]
	v_pk_fma_f32 v[108:109], v[108:109], v[164:165], v[168:169]
	global_store_dwordx4 v[122:123], v[108:111], off sc1
	s_waitcnt vmcnt(5) lgkmcnt(0)
	v_pk_fma_f32 v[106:107], v[106:107], v[174:175], v[178:179]
	v_pk_fma_f32 v[104:105], v[104:105], v[172:173], v[176:177]
	global_store_dwordx4 v[122:123], v[104:107], off offset:64 sc1
	s_waitcnt vmcnt(4) lgkmcnt(0)
	v_pk_fma_f32 v[102:103], v[102:103], v[182:183], v[186:187]
	v_pk_fma_f32 v[100:101], v[100:101], v[180:181], v[184:185]
	global_store_dwordx4 v[122:123], v[100:103], off offset:512 sc1
	s_waitcnt vmcnt(3) lgkmcnt(0)
	v_pk_fma_f32 v[98:99], v[98:99], v[190:191], v[194:195]
	v_pk_fma_f32 v[96:97], v[96:97], v[188:189], v[192:193]
	global_store_dwordx4 v[122:123], v[96:99], off offset:576 sc1
	s_nop 1
	v_or_b32_e32 v96, 32, v142
	v_min_i32_e32 v97, 0x8000, v96
	v_cmp_gt_i32_e32 vcc, s97, v96
	v_ashrrev_i32_e32 v100, 13, v97
	v_ashrrev_i32_e32 v97, 31, v96
	v_add_u32_e32 v98, 0xffff8020, v142
	v_cndmask_b32_e32 v97, 0, v97, vcc
	v_cndmask_b32_e32 v96, v98, v96, vcc
	v_cndmask_b32_e32 v99, v140, v141, vcc
	v_cndmask_b32_e32 v98, v143, v144, vcc
	v_lshlrev_b64 v[96:97], 12, v[96:97]
	v_lshl_add_u64 v[98:99], v[98:99], 0, v[96:97]
	v_lshl_add_u64 v[104:105], v[98:99], 0, v[134:135]
	v_cndmask_b32_e32 v99, v145, v146, vcc
	v_cndmask_b32_e32 v98, v147, v148, vcc
	v_lshl_add_u64 v[96:97], v[98:99], 0, v[96:97]
	v_lshl_add_u64 v[106:107], v[96:97], 0, v[134:135]
	v_mul_i32_i24_e32 v96, 0x1800, v100
	v_ashrrev_i32_e32 v97, 31, v96
	v_lshl_add_u64 v[96:97], v[96:97], 2, s[6:7]
	v_lshl_add_u64 v[108:109], v[96:97], 0, v[134:135]
	global_load_dwordx4 v[164:167], v[108:109], off
	global_load_dwordx4 v[168:171], v[104:105], off
	global_load_dwordx4 v[172:175], v[108:109], off offset:64
	global_load_dwordx4 v[176:179], v[104:105], off offset:64
	global_load_dwordx4 v[180:183], v[108:109], off offset:512
	global_load_dwordx4 v[184:187], v[104:105], off offset:512
	global_load_dwordx4 v[188:191], v[108:109], off offset:576
	global_load_dwordx4 v[192:195], v[104:105], off offset:576
	s_waitcnt vmcnt(6) lgkmcnt(0)
;     __device__ __forceinline__ void operator()(const pg8::f32x4 (&acc)[2][2][4][2], const pg8::Unit& u, int wr, int wc, int fr, int fq) const {
;         const int col0 = u.pn * 256 + wc * 32 + 4 * fq;
; #pragma unroll
;         for (int ai = 0; ai < 2; ++ai)
; #pragma unroll
;             for (int m = 0; m < 4; ++m) {
;                 const int r = row_off + u.pm * 256 + ai * 128 + wr * 64 + m * 16 + fr;
;                 const bool lat = r < ML; const int bi = lat ? (r >> 13) : 4;
;                 const size_t off = lat ? (size_t)r * 1024 : (size_t)(r - ML) * 1024;
;                 const float* bp = (lat ? base_lat : base_ctx) + off + col0; float* op = (lat ? out_lat : out_ctx) + off + col0;
;                 const float* gp = gate + bi * 6144 + col0;
; #pragma unroll
;                 for (int bj = 0; bj < 2; ++bj)
; #pragma unroll
;                     for (int n = 0; n < 2; ++n) {
;                         const pg8::f32x4 g4 = *(const pg8::f32x4*)(gp + bj * 128 + n * 16), b4 = *(const pg8::f32x4*)(bp + bj * 128 + n * 16);
;                         *(pg8::f32x4*)(op + bj * 128 + n * 16) = b4 + g4 * acc[ai][bj][m][n];
;                     }
;             }
;     }
	v_pk_fma_f32 v[94:95], v[94:95], v[166:167], v[170:171]
	v_pk_fma_f32 v[92:93], v[92:93], v[164:165], v[168:169]
	global_store_dwordx4 v[106:107], v[92:95], off sc1
	s_waitcnt vmcnt(5) lgkmcnt(0)
	v_pk_fma_f32 v[90:91], v[90:91], v[174:175], v[178:179]
	v_pk_fma_f32 v[88:89], v[88:89], v[172:173], v[176:177]
	global_store_dwordx4 v[106:107], v[88:91], off offset:64 sc1
	s_waitcnt vmcnt(4) lgkmcnt(0)
	v_pk_fma_f32 v[86:87], v[86:87], v[182:183], v[186:187]
	v_pk_fma_f32 v[84:85], v[84:85], v[180:181], v[184:185]
	global_store_dwordx4 v[106:107], v[84:87], off offset:512 sc1
	s_waitcnt vmcnt(3) lgkmcnt(0)
	v_pk_fma_f32 v[82:83], v[82:83], v[190:191], v[194:195]
	v_pk_fma_f32 v[80:81], v[80:81], v[188:189], v[192:193]
	global_store_dwordx4 v[106:107], v[80:83], off offset:576 sc1
	s_nop 1
	v_or_b32_e32 v80, 48, v142
	v_min_i32_e32 v81, 0x8000, v80
	v_cmp_gt_i32_e32 vcc, s97, v80
	v_ashrrev_i32_e32 v84, 13, v81
	v_ashrrev_i32_e32 v81, 31, v80
	v_add_u32_e32 v82, 0xffff8030, v142
	v_cndmask_b32_e32 v81, 0, v81, vcc
	v_cndmask_b32_e32 v80, v82, v80, vcc
	v_cndmask_b32_e32 v83, v140, v141, vcc
	v_cndmask_b32_e32 v82, v143, v144, vcc
	v_lshlrev_b64 v[80:81], 12, v[80:81]
	v_lshl_add_u64 v[82:83], v[82:83], 0, v[80:81]
	v_lshl_add_u64 v[88:89], v[82:83], 0, v[134:135]
	v_cndmask_b32_e32 v83, v145, v146, vcc
	v_cndmask_b32_e32 v82, v147, v148, vcc
	v_lshl_add_u64 v[80:81], v[82:83], 0, v[80:81]
	v_lshl_add_u64 v[90:91], v[80:81], 0, v[134:135]
	v_mul_i32_i24_e32 v80, 0x1800, v84
	v_ashrrev_i32_e32 v81, 31, v80
	v_lshl_add_u64 v[80:81], v[80:81], 2, s[6:7]
	v_lshl_add_u64 v[92:93], v[80:81], 0, v[134:135]
	global_load_dwordx4 v[164:167], v[92:93], off
	global_load_dwordx4 v[168:171], v[88:89], off
	global_load_dwordx4 v[172:175], v[92:93], off offset:64
	global_load_dwordx4 v[176:179], v[88:89], off offset:64
	global_load_dwordx4 v[180:183], v[92:93], off offset:512
	global_load_dwordx4 v[184:187], v[88:89], off offset:512
	global_load_dwordx4 v[188:191], v[92:93], off offset:576
	global_load_dwordx4 v[192:195], v[88:89], off offset:576
	s_waitcnt vmcnt(6) lgkmcnt(0)
	v_pk_fma_f32 v[78:79], v[78:79], v[166:167], v[170:171]
	v_pk_fma_f32 v[76:77], v[76:77], v[164:165], v[168:169]
	global_store_dwordx4 v[90:91], v[76:79], off sc1
	s_waitcnt vmcnt(5) lgkmcnt(0)
	v_pk_fma_f32 v[74:75], v[74:75], v[174:175], v[178:179]
	v_pk_fma_f32 v[72:73], v[72:73], v[172:173], v[176:177]
	global_store_dwordx4 v[90:91], v[72:75], off offset:64 sc1
	s_waitcnt vmcnt(4) lgkmcnt(0)
	v_pk_fma_f32 v[70:71], v[70:71], v[182:183], v[186:187]
	v_pk_fma_f32 v[68:69], v[68:69], v[180:181], v[184:185]
	global_store_dwordx4 v[90:91], v[68:71], off offset:512 sc1
	s_waitcnt vmcnt(3) lgkmcnt(0)
	v_pk_fma_f32 v[66:67], v[66:67], v[190:191], v[194:195]
	v_pk_fma_f32 v[64:65], v[64:65], v[188:189], v[192:193]
	global_store_dwordx4 v[90:91], v[64:67], off offset:576 sc1
	s_nop 1
	v_add_u32_e32 v64, 0x80, v142
	v_min_i32_e32 v65, 0x8000, v64
	v_cmp_gt_i32_e32 vcc, s97, v64
	v_ashrrev_i32_e32 v68, 13, v65
	v_ashrrev_i32_e32 v65, 31, v64
	v_add_u32_e32 v66, 0xffff8080, v142
	v_cndmask_b32_e32 v65, 0, v65, vcc
	v_cndmask_b32_e32 v64, v66, v64, vcc
	v_cndmask_b32_e32 v67, v140, v141, vcc
	v_cndmask_b32_e32 v66, v143, v144, vcc
	v_lshlrev_b64 v[64:65], 12, v[64:65]
	v_lshl_add_u64 v[66:67], v[66:67], 0, v[64:65]
	v_lshl_add_u64 v[72:73], v[66:67], 0, v[134:135]
	v_cndmask_b32_e32 v67, v145, v146, vcc
	v_cndmask_b32_e32 v66, v147, v148, vcc
	v_lshl_add_u64 v[64:65], v[66:67], 0, v[64:65]
	v_lshl_add_u64 v[74:75], v[64:65], 0, v[134:135]
	v_mul_i32_i24_e32 v64, 0x1800, v68
	v_ashrrev_i32_e32 v65, 31, v64
	v_lshl_add_u64 v[64:65], v[64:65], 2, s[6:7]
	v_lshl_add_u64 v[76:77], v[64:65], 0, v[134:135]
	global_load_dwordx4 v[164:167], v[76:77], off
	global_load_dwordx4 v[168:171], v[72:73], off
	global_load_dwordx4 v[172:175], v[76:77], off offset:64
	global_load_dwordx4 v[176:179], v[72:73], off offset:64
	global_load_dwordx4 v[180:183], v[76:77], off offset:512
	global_load_dwordx4 v[184:187], v[72:73], off offset:512
	global_load_dwordx4 v[188:191], v[76:77], off offset:576
	global_load_dwordx4 v[192:195], v[72:73], off offset:576
	s_waitcnt vmcnt(6) lgkmcnt(0)
	v_pk_fma_f32 v[62:63], v[62:63], v[166:167], v[170:171]
	v_pk_fma_f32 v[60:61], v[60:61], v[164:165], v[168:169]
	global_store_dwordx4 v[74:75], v[60:63], off sc1
	s_waitcnt vmcnt(5) lgkmcnt(0)
	v_pk_fma_f32 v[58:59], v[58:59], v[174:175], v[178:179]
	v_pk_fma_f32 v[56:57], v[56:57], v[172:173], v[176:177]
	global_store_dwordx4 v[74:75], v[56:59], off offset:64 sc1
	s_waitcnt vmcnt(4) lgkmcnt(0)
	v_pk_fma_f32 v[54:55], v[54:55], v[182:183], v[186:187]
	v_pk_fma_f32 v[52:53], v[52:53], v[180:181], v[184:185]
	global_store_dwordx4 v[74:75], v[52:55], off offset:512 sc1
	s_waitcnt vmcnt(3) lgkmcnt(0)
	v_pk_fma_f32 v[50:51], v[50:51], v[190:191], v[194:195]
	v_pk_fma_f32 v[48:49], v[48:49], v[188:189], v[192:193]
	global_store_dwordx4 v[74:75], v[48:51], off offset:576 sc1
	s_nop 1
	v_add_u32_e32 v48, 0x90, v142
	v_min_i32_e32 v49, 0x8000, v48
	v_cmp_gt_i32_e32 vcc, s97, v48
	v_ashrrev_i32_e32 v52, 13, v49
	v_ashrrev_i32_e32 v49, 31, v48
	v_add_u32_e32 v50, 0xffff8090, v142
	v_cndmask_b32_e32 v49, 0, v49, vcc
	v_cndmask_b32_e32 v48, v50, v48, vcc
	v_cndmask_b32_e32 v51, v140, v141, vcc
	v_cndmask_b32_e32 v50, v143, v144, vcc
	v_lshlrev_b64 v[48:49], 12, v[48:49]
	v_lshl_add_u64 v[50:51], v[50:51], 0, v[48:49]
	v_lshl_add_u64 v[56:57], v[50:51], 0, v[134:135]
	v_cndmask_b32_e32 v51, v145, v146, vcc
	v_cndmask_b32_e32 v50, v147, v148, vcc
	v_lshl_add_u64 v[48:49], v[50:51], 0, v[48:49]
	v_lshl_add_u64 v[58:59], v[48:49], 0, v[134:135]
	v_mul_i32_i24_e32 v48, 0x1800, v52
	v_ashrrev_i32_e32 v49, 31, v48
	v_lshl_add_u64 v[48:49], v[48:49], 2, s[6:7]
	v_lshl_add_u64 v[60:61], v[48:49], 0, v[134:135]
	global_load_dwordx4 v[164:167], v[60:61], off
	global_load_dwordx4 v[168:171], v[56:57], off
	global_load_dwordx4 v[172:175], v[60:61], off offset:64
	global_load_dwordx4 v[176:179], v[56:57], off offset:64
	global_load_dwordx4 v[180:183], v[60:61], off offset:512
	global_load_dwordx4 v[184:187], v[56:57], off offset:512
	global_load_dwordx4 v[188:191], v[60:61], off offset:576
	global_load_dwordx4 v[192:195], v[56:57], off offset:576
	s_waitcnt vmcnt(6) lgkmcnt(0)
; #define PG8_BAR __builtin_amdgcn_s_barrier()
; template <class Epi, class Sched, bool ALIGN_EPI = false, bool SP2 = false, bool HALO = false>
; __device__ __forceinline__ void gemm_phase(PG8_LAS unsigned char* lds, const Gemm g, const Sched& S, const Epi& E, const int wave0) {
;     ...
;         if constexpr (ALIGN_EPI) { if (wr == 1) PG8_BAR; }
;     __device__ __forceinline__ void operator()(const pg8::f32x4 (&acc)[2][2][4][2], const pg8::Unit& u, int wr, int wc, int fr, int fq) const {
;         const int col0 = u.pn * 256 + wc * 32 + 4 * fq;
; #pragma unroll
;         for (int ai = 0; ai < 2; ++ai)
; #pragma unroll
;             for (int m = 0; m < 4; ++m) {
;                 const int r = row_off + u.pm * 256 + ai * 128 + wr * 64 + m * 16 + fr;
;                 const bool lat = r < ML; const int bi = lat ? (r >> 13) : 4;
;                 const size_t off = lat ? (size_t)r * 1024 : (size_t)(r - ML) * 1024;
;                 const float* bp = (lat ? base_lat : base_ctx) + off + col0; float* op = (lat ? out_lat : out_ctx) + off + col0;
;                 const float* gp = gate + bi * 6144 + col0;
; #pragma unroll
;                 for (int bj = 0; bj < 2; ++bj)
; #pragma unroll
;                     for (int n = 0; n < 2; ++n) {
;                         const pg8::f32x4 g4 = *(const pg8::f32x4*)(gp + bj * 128 + n * 16), b4 = *(const pg8::f32x4*)(bp + bj * 128 + n * 16);
;                         *(pg8::f32x4*)(op + bj * 128 + n * 16) = b4 + g4 * acc[ai][bj][m][n];
;                     }
;             }
;     }
	v_pk_fma_f32 v[46:47], v[46:47], v[166:167], v[170:171]
	v_pk_fma_f32 v[44:45], v[44:45], v[164:165], v[168:169]
	global_store_dwordx4 v[58:59], v[44:47], off sc1
	s_waitcnt vmcnt(5) lgkmcnt(0)
	v_pk_fma_f32 v[42:43], v[42:43], v[174:175], v[178:179]
	v_pk_fma_f32 v[40:41], v[40:41], v[172:173], v[176:177]
	global_store_dwordx4 v[58:59], v[40:43], off offset:64 sc1
	s_waitcnt vmcnt(4) lgkmcnt(0)
	v_pk_fma_f32 v[38:39], v[38:39], v[182:183], v[186:187]
	v_pk_fma_f32 v[36:37], v[36:37], v[180:181], v[184:185]
	global_store_dwordx4 v[58:59], v[36:39], off offset:512 sc1
	s_waitcnt vmcnt(3) lgkmcnt(0)
	v_pk_fma_f32 v[34:35], v[34:35], v[190:191], v[194:195]
	v_pk_fma_f32 v[32:33], v[32:33], v[188:189], v[192:193]
	global_store_dwordx4 v[58:59], v[32:35], off offset:576 sc1
	s_nop 1
	v_add_u32_e32 v32, 0xa0, v142
	v_min_i32_e32 v33, 0x8000, v32
	v_cmp_gt_i32_e32 vcc, s97, v32
	v_ashrrev_i32_e32 v36, 13, v33
	v_ashrrev_i32_e32 v33, 31, v32
	v_add_u32_e32 v34, 0xffff80a0, v142
	v_cndmask_b32_e32 v33, 0, v33, vcc
	v_cndmask_b32_e32 v32, v34, v32, vcc
	v_cndmask_b32_e32 v35, v140, v141, vcc
	v_cndmask_b32_e32 v34, v143, v144, vcc
	v_lshlrev_b64 v[32:33], 12, v[32:33]
	v_lshl_add_u64 v[34:35], v[34:35], 0, v[32:33]
	v_lshl_add_u64 v[40:41], v[34:35], 0, v[134:135]
	v_cndmask_b32_e32 v35, v145, v146, vcc
	v_cndmask_b32_e32 v34, v147, v148, vcc
	v_lshl_add_u64 v[32:33], v[34:35], 0, v[32:33]
	v_lshl_add_u64 v[42:43], v[32:33], 0, v[134:135]
	v_mul_i32_i24_e32 v32, 0x1800, v36
	v_ashrrev_i32_e32 v33, 31, v32
	v_lshl_add_u64 v[32:33], v[32:33], 2, s[6:7]
	v_lshl_add_u64 v[44:45], v[32:33], 0, v[134:135]
	global_load_dwordx4 v[164:167], v[44:45], off
	global_load_dwordx4 v[168:171], v[40:41], off
	global_load_dwordx4 v[172:175], v[44:45], off offset:64
	global_load_dwordx4 v[176:179], v[40:41], off offset:64
	global_load_dwordx4 v[180:183], v[44:45], off offset:512
	global_load_dwordx4 v[184:187], v[40:41], off offset:512
	global_load_dwordx4 v[188:191], v[44:45], off offset:576
	global_load_dwordx4 v[192:195], v[40:41], off offset:576
	s_waitcnt vmcnt(6) lgkmcnt(0)
	v_pk_fma_f32 v[30:31], v[30:31], v[166:167], v[170:171]
	v_pk_fma_f32 v[28:29], v[28:29], v[164:165], v[168:169]
	global_store_dwordx4 v[42:43], v[28:31], off sc1
	s_waitcnt vmcnt(5) lgkmcnt(0)
	v_pk_fma_f32 v[26:27], v[26:27], v[174:175], v[178:179]
	v_pk_fma_f32 v[24:25], v[24:25], v[172:173], v[176:177]
	global_store_dwordx4 v[42:43], v[24:27], off offset:64 sc1
	s_waitcnt vmcnt(4) lgkmcnt(0)
	v_pk_fma_f32 v[22:23], v[22:23], v[182:183], v[186:187]
	v_pk_fma_f32 v[20:21], v[20:21], v[180:181], v[184:185]
	global_store_dwordx4 v[42:43], v[20:23], off offset:512 sc1
	s_waitcnt vmcnt(3) lgkmcnt(0)
	v_pk_fma_f32 v[18:19], v[18:19], v[190:191], v[194:195]
	v_pk_fma_f32 v[16:17], v[16:17], v[188:189], v[192:193]
	global_store_dwordx4 v[42:43], v[16:19], off offset:576 sc1
	s_nop 1
	v_add_u32_e32 v16, 0xb0, v142
	v_min_i32_e32 v17, 0x8000, v16
	v_cmp_gt_i32_e32 vcc, s97, v16
	v_ashrrev_i32_e32 v20, 13, v17
	v_ashrrev_i32_e32 v17, 31, v16
	v_add_u32_e32 v18, 0xffff80b0, v142
	v_cndmask_b32_e32 v17, 0, v17, vcc
	v_cndmask_b32_e32 v16, v18, v16, vcc
	v_cndmask_b32_e32 v19, v140, v141, vcc
	v_cndmask_b32_e32 v18, v143, v144, vcc
	v_lshlrev_b64 v[16:17], 12, v[16:17]
	v_lshl_add_u64 v[18:19], v[18:19], 0, v[16:17]
	v_lshl_add_u64 v[24:25], v[18:19], 0, v[134:135]
	v_cndmask_b32_e32 v19, v145, v146, vcc
	v_cndmask_b32_e32 v18, v147, v148, vcc
	v_lshl_add_u64 v[16:17], v[18:19], 0, v[16:17]
	v_lshl_add_u64 v[26:27], v[16:17], 0, v[134:135]
	v_mul_i32_i24_e32 v16, 0x1800, v20
	v_ashrrev_i32_e32 v17, 31, v16
	v_lshl_add_u64 v[16:17], v[16:17], 2, s[6:7]
	v_lshl_add_u64 v[28:29], v[16:17], 0, v[134:135]
	global_load_dwordx4 v[164:167], v[28:29], off
	global_load_dwordx4 v[168:171], v[24:25], off
	global_load_dwordx4 v[172:175], v[28:29], off offset:64
	global_load_dwordx4 v[176:179], v[24:25], off offset:64
	global_load_dwordx4 v[180:183], v[28:29], off offset:512
	global_load_dwordx4 v[184:187], v[24:25], off offset:512
	global_load_dwordx4 v[188:191], v[28:29], off offset:576
	global_load_dwordx4 v[192:195], v[24:25], off offset:576
	s_andn2_b64 vcc, exec, s[38:39]
	s_waitcnt vmcnt(6) lgkmcnt(0)
	v_pk_fma_f32 v[14:15], v[14:15], v[166:167], v[170:171]
	v_pk_fma_f32 v[12:13], v[12:13], v[164:165], v[168:169]
	global_store_dwordx4 v[26:27], v[12:15], off sc1
	s_waitcnt vmcnt(5) lgkmcnt(0)
	v_pk_fma_f32 v[10:11], v[10:11], v[174:175], v[178:179]
	v_pk_fma_f32 v[8:9], v[8:9], v[172:173], v[176:177]
	global_store_dwordx4 v[26:27], v[8:11], off offset:64 sc1
	s_waitcnt vmcnt(4) lgkmcnt(0)
	v_pk_fma_f32 v[6:7], v[6:7], v[182:183], v[186:187]
	v_pk_fma_f32 v[4:5], v[4:5], v[180:181], v[184:185]
	global_store_dwordx4 v[26:27], v[4:7], off offset:512 sc1
	s_waitcnt vmcnt(3) lgkmcnt(0)
	v_pk_fma_f32 v[2:3], v[2:3], v[190:191], v[194:195]
	v_pk_fma_f32 v[0:1], v[0:1], v[188:189], v[192:193]
	global_store_dwordx4 v[26:27], v[0:3], off offset:576 sc1
	s_cbranch_vccnz .LBB0_914
	s_andn2_b64 vcc, exec, s[4:5]
	s_cbranch_vccnz .LBB0_913
	s_barrier
	s_branch .LBB0_913

; __device__ __forceinline__ float dpp_ror1(float v) { return __builtin_bit_cast(float, __builtin_amdgcn_update_dpp(0, __builtin_bit_cast(int, v), 0x121, 0xF, 0xF, false)); }
;     __device__ __forceinline__ void operator()(const pg8::f32x4 (&acc)[2][2][4][2], const pg8::Unit& u, int wr, int wc, int fr, int fq) const {
;         const int ch0 = u.pn * 128 + wc * 32 + 8 * fq;
;         float w0[8], w1[8], w2[8], bb[8];
; #pragma unroll
;         for (int hq = 0; hq < 2; ++hq) { const pg8::f32x4 q0 = *(const pg8::f32x4*)(cw + ch0 + 4 * hq), q1 = *(const pg8::f32x4*)(cw + DFF + ch0 + 4 * hq), q2 = *(const pg8::f32x4*)(cw + 2 * DFF + ch0 + 4 * hq), q3 = *(const pg8::f32x4*)(cb + ch0 + 4 * hq);
; #pragma unroll
;             for (int e = 0; e < 4; ++e) { w0[4 * hq + e] = q0[e]; w1[4 * hq + e] = q1[e]; w2[4 * hq + e] = q2[e]; bb[4 * hq + e] = q3[e]; } }
; #pragma unroll
;         for (int ai = 0; ai < 2; ++ai) {
;             const int kb = u.pm * 4 + ai * 2 + wr;
;             float ruP[8], rdC[8];
; #pragma unroll
;             for (int c = 0; c < 8; ++c) { ruP[c] = 0.f; rdC[c] = dpp_rol1(acc[ai][0][0][c >> 2][c & 3]); }
; #pragma unroll
;             for (int m = 0; m < 4; ++m) {
;                 const int rl = 16 * m + fr, gr = 62 * kb - 1 + rl;
;                 bool first, last; if (gr < ML) { const int t = gr & 8191; first = t == 0; last = t == 8191; } else { const int t = (gr - ML) & 255; first = t == 0; last = t == 255; }
;                 float res[8];
; #pragma unroll
;                 for (int c = 0; c < 8; ++c) {
;                     const int n = c >> 2, e = c & 3;
;                     const float x0 = acc[ai][0][m][n][e];
;                     const float ruC = dpp_ror1(x0), rdN = m < 3 ? dpp_rol1(acc[ai][0][m < 3 ? m + 1 : 3][n][e]) : 0.f;
;                     float xu = fr == 0 ? ruP[c] : ruC, xd = fr == 15 ? rdN : rdC[c];
;                     xu = first ? 0.f : xu; xd = last ? 0.f : xd;
;                     ruP[c] = ruC; rdC[c] = rdN;
;                     const float x = w0[c] * xu + w1[c] * x0 + w2[c] * xd + bb[c];
;                     const float u2 = -2.302208198f * (x + 0.044715f * x * x * x);
;                     res[c] = x * __builtin_amdgcn_rcpf(1.0f + __builtin_amdgcn_exp2f(u2)) * acc[ai][1][m][n][e];
.LBB0_1084:
	v_lshl_or_b32 v170, s52, 7, v177
	v_ashrrev_i32_e32 v171, 31, v170
	v_lshlrev_b64 v[56:57], 2, v[170:171]
	v_lshl_add_u64 v[60:61], s[10:11], 0, v[56:57]
	v_lshl_add_u64 v[62:63], s[68:69], 0, v[56:57]
	v_lshl_add_u64 v[64:65], s[70:71], 0, v[56:57]
	v_lshl_add_u64 v[84:85], s[36:37], 0, v[56:57]
	global_load_dwordx4 v[56:59], v[60:61], off offset:16
	global_load_dwordx4 v[76:79], v[60:61], off
	global_load_dwordx4 v[68:71], v[62:63], off offset:16
	global_load_dwordx4 v[92:95], v[62:63], off
	s_nop 0
	global_load_dwordx4 v[60:63], v[64:65], off offset:16
	global_load_dwordx4 v[80:83], v[64:65], off
	s_nop 0
	global_load_dwordx4 v[64:67], v[84:85], off offset:16
	s_nop 0
	global_load_dwordx4 v[84:87], v[84:85], off
	s_lshl_b32 s12, s65, 2
	s_add_i32 s65, s12, s88
	s_mul_i32 s65, s65, 62
	s_add_i32 s73, s65, -1
	v_add_u32_e32 v194, s73, v172
	v_cmp_gt_i32_e32 vcc, s86, v194
	v_mov_b32_dpp v198, v152 row_ror:15 row_mask:0xf bank_mask:0xf
	v_mov_b32_dpp v199, v153 row_ror:15 row_mask:0xf bank_mask:0xf
	v_mov_b32_dpp v200, v154 row_ror:15 row_mask:0xf bank_mask:0xf
	v_mov_b32_dpp v201, v155 row_ror:15 row_mask:0xf bank_mask:0xf
	v_mov_b32_dpp v202, v156 row_ror:15 row_mask:0xf bank_mask:0xf
	v_mov_b32_dpp v203, v157 row_ror:15 row_mask:0xf bank_mask:0xf
	v_mov_b32_dpp v196, v158 row_ror:15 row_mask:0xf bank_mask:0xf
	v_mov_b32_dpp v197, v159 row_ror:15 row_mask:0xf bank_mask:0xf
	v_mov_b32_dpp v184, v152 row_ror:1 row_mask:0xf bank_mask:0xf
	v_mov_b32_dpp v183, v140 row_ror:15 row_mask:0xf bank_mask:0xf
	v_mov_b32_dpp v181, v153 row_ror:1 row_mask:0xf bank_mask:0xf
	v_mov_b32_dpp v179, v141 row_ror:15 row_mask:0xf bank_mask:0xf
	v_mov_b32_dpp v188, v154 row_ror:1 row_mask:0xf bank_mask:0xf
	v_mov_b32_dpp v187, v142 row_ror:15 row_mask:0xf bank_mask:0xf
	v_mov_b32_dpp v186, v155 row_ror:1 row_mask:0xf bank_mask:0xf
	v_mov_b32_dpp v185, v143 row_ror:15 row_mask:0xf bank_mask:0xf
	v_mov_b32_dpp v192, v156 row_ror:1 row_mask:0xf bank_mask:0xf
	v_mov_b32_dpp v191, v136 row_ror:15 row_mask:0xf bank_mask:0xf
	v_mov_b32_dpp v190, v157 row_ror:1 row_mask:0xf bank_mask:0xf
	v_mov_b32_dpp v189, v137 row_ror:15 row_mask:0xf bank_mask:0xf
	v_mov_b32_dpp v195, v158 row_ror:1 row_mask:0xf bank_mask:0xf
	v_mov_b32_dpp v193, v138 row_ror:15 row_mask:0xf bank_mask:0xf
	v_mov_b32_dpp v182, v159 row_ror:1 row_mask:0xf bank_mask:0xf
	v_mov_b32_dpp v180, v139 row_ror:15 row_mask:0xf bank_mask:0xf
	s_and_b64 s[48:49], s[42:43], vcc
	s_and_saveexec_b64 s[52:53], s[48:49]
	s_movk_i32 s12, 0xff
	s_movk_i32 s78, 0x1fff
	s_cbranch_execz .LBB0_1086
	v_and_b32_e32 v204, 0x1fff, v194
	v_and_b32_e32 v205, 0xff, v194
	v_cmp_gt_i32_e32 vcc, s97, v194
	v_cmp_eq_u32_e64 s[48:49], s78, v204
	s_waitcnt vmcnt(0)
	v_pk_mul_f32 v[156:157], v[156:157], v[68:69]
	v_cndmask_b32_e32 v206, v205, v204, vcc
	v_cndmask_b32_e64 v204, 0, 1, s[48:49]
	v_cmp_eq_u32_e64 s[48:49], s12, v205
	v_cndmask_b32_e64 v202, v202, v191, s[40:41]
	v_cndmask_b32_e64 v203, v203, v189, s[40:41]
	v_cndmask_b32_e64 v205, 0, 1, s[48:49]
	v_cndmask_b32_e32 v204, v205, v204, vcc
	v_and_b32_e32 v207, 1, v204
	v_cmp_eq_u32_e32 vcc, 0, v206
	v_cmp_eq_u32_e64 s[48:49], 1, v207
	v_pk_mul_f32 v[152:153], v[152:153], v[92:93]
	v_cndmask_b32_e64 v205, v190, 0, vcc
	v_cndmask_b32_e64 v204, v192, 0, vcc
	v_pk_fma_f32 v[156:157], v[56:57], v[204:205], v[156:157]
	v_cndmask_b32_e64 v203, v203, 0, s[48:49]
	v_cndmask_b32_e64 v202, v202, 0, s[48:49]
	v_pk_fma_f32 v[156:157], v[60:61], v[202:203], v[156:157]
	v_cndmask_b32_e64 v198, v198, v183, s[40:41]
	v_pk_add_f32 v[156:157], v[64:65], v[156:157]
	v_cndmask_b32_e64 v199, v199, v179, s[40:41]
	v_mul_f32_e32 v202, 0x3d372713, v156
	v_mul_f32_e32 v203, 0x3d372713, v157
	v_mul_f32_e32 v202, v156, v202
	v_mul_f32_e32 v203, v157, v203
	v_fma_f32 v202, v156, v202, v156
	v_fma_f32 v203, v157, v203, v157
	v_mul_f32_e32 v202, 0xc0135761, v202
	v_mul_f32_e32 v203, 0xc0135761, v203
	v_exp_f32_e32 v202, v202
	v_exp_f32_e32 v203, v203
	v_cndmask_b32_e64 v199, v199, 0, s[48:49]
	v_cndmask_b32_e64 v198, v198, 0, s[48:49]
	v_add_f32_e32 v202, 1.0, v202
	v_add_f32_e32 v203, 1.0, v203
	v_rcp_f32_e32 v202, v202
	v_rcp_f32_e32 v203, v203
	v_pk_mul_f32 v[158:159], v[158:159], v[70:71]
	v_cndmask_b32_e64 v196, v196, v193, s[40:41]
	v_cndmask_b32_e64 v197, v197, v180, s[40:41]
	v_pk_mul_f32 v[156:157], v[156:157], v[202:203]
	v_cndmask_b32_e64 v197, v197, 0, s[48:49]
	v_pk_mul_f32 v[156:157], v[144:145], v[156:157]
	v_pk_mul_f32 v[144:145], v[154:155], v[94:95]
	v_cndmask_b32_e64 v155, v186, 0, vcc
	v_cndmask_b32_e64 v154, v188, 0, vcc
	v_pk_fma_f32 v[144:145], v[78:79], v[154:155], v[144:145]
	v_cndmask_b32_e64 v154, v200, v187, s[40:41]
	v_cndmask_b32_e64 v155, v201, v185, s[40:41]
	v_cndmask_b32_e64 v155, v155, 0, s[48:49]
	v_cndmask_b32_e64 v154, v154, 0, s[48:49]
	v_pk_fma_f32 v[144:145], v[82:83], v[154:155], v[144:145]
	v_cndmask_b32_e64 v201, v181, 0, vcc
	v_pk_add_f32 v[144:145], v[86:87], v[144:145]
	v_cndmask_b32_e64 v200, v184, 0, vcc
	v_mul_f32_e32 v154, 0x3d372713, v144
	v_mul_f32_e32 v155, 0x3d372713, v145
	v_mul_f32_e32 v154, v144, v154
	v_mul_f32_e32 v155, v145, v155
	v_fma_f32 v154, v144, v154, v144
	v_fma_f32 v155, v145, v155, v145
	v_pk_fma_f32 v[152:153], v[76:77], v[200:201], v[152:153]
	v_mul_f32_e32 v154, 0xc0135761, v154
	v_mul_f32_e32 v155, 0xc0135761, v155
	v_pk_fma_f32 v[152:153], v[80:81], v[198:199], v[152:153]
	v_exp_f32_e32 v154, v154
	v_exp_f32_e32 v155, v155
	v_pk_add_f32 v[152:153], v[84:85], v[152:153]
	v_cndmask_b32_e64 v196, v196, 0, s[48:49]
	v_mul_f32_e32 v198, 0x3d372713, v152
	v_mul_f32_e32 v199, 0x3d372713, v153
	v_mul_f32_e32 v198, v152, v198
; __device__ __forceinline__ unsigned pk2(float lo, float hi) { const f32x2_cv v = {lo, hi}; const bf16x2_cv b = __builtin_convertvector(v, bf16x2_cv); return __builtin_bit_cast(unsigned, b); }
; __device__ __forceinline__ float dpp_ror1(float v) { return __builtin_bit_cast(float, __builtin_amdgcn_update_dpp(0, __builtin_bit_cast(int, v), 0x121, 0xF, 0xF, false)); }
; __device__ __forceinline__ float dpp_rol1(float v) { return __builtin_bit_cast(float, __builtin_amdgcn_update_dpp(0, __builtin_bit_cast(int, v), 0x12F, 0xF, 0xF, false)); }
;     __device__ __forceinline__ void operator()(const pg8::f32x4 (&acc)[2][2][4][2], const pg8::Unit& u, int wr, int wc, int fr, int fq) const {
;     ...
;                 for (int c = 0; c < 8; ++c) {
;                     const int n = c >> 2, e = c & 3;
;                     const float x0 = acc[ai][0][m][n][e];
;                     const float ruC = dpp_ror1(x0), rdN = m < 3 ? dpp_rol1(acc[ai][0][m < 3 ? m + 1 : 3][n][e]) : 0.f;
;                     float xu = fr == 0 ? ruP[c] : ruC, xd = fr == 15 ? rdN : rdC[c];
;                     xu = first ? 0.f : xu; xd = last ? 0.f : xd;
;                     ruP[c] = ruC; rdC[c] = rdN;
;                     const float x = w0[c] * xu + w1[c] * x0 + w2[c] * xd + bb[c];
;                     const float u2 = -2.302208198f * (x + 0.044715f * x * x * x);
;                     res[c] = x * __builtin_amdgcn_rcpf(1.0f + __builtin_amdgcn_exp2f(u2)) * acc[ai][1][m][n][e];
;                 }
;                 if (rl >= 1 && rl <= 62 && gr < nrows) { v4u o; o.x = pk2(res[0], res[1]); o.y = pk2(res[2], res[3]); o.z = pk2(res[4], res[5]); o.w = pk2(res[6], res[7]);
;                     *(v4u*)(G + (size_t)gr * DFF + ch0) = o; }
	v_mul_f32_e32 v199, v153, v199
	v_fma_f32 v198, v152, v198, v152
	v_fma_f32 v199, v153, v199, v153
	v_add_f32_e32 v154, 1.0, v154
	v_add_f32_e32 v155, 1.0, v155
	v_mul_f32_e32 v198, 0xc0135761, v198
	v_mul_f32_e32 v199, 0xc0135761, v199
	v_rcp_f32_e32 v154, v154
	v_rcp_f32_e32 v155, v155
	v_exp_f32_e32 v198, v198
	v_exp_f32_e32 v199, v199
	v_pk_mul_f32 v[144:145], v[144:145], v[154:155]
	v_add_f32_e32 v154, 1.0, v198
	v_add_f32_e32 v155, 1.0, v199
	v_cndmask_b32_e64 v199, v182, 0, vcc
	v_cndmask_b32_e64 v198, v195, 0, vcc
	v_pk_fma_f32 v[158:159], v[58:59], v[198:199], v[158:159]
	v_rcp_f32_e32 v154, v154
	v_pk_fma_f32 v[158:159], v[62:63], v[196:197], v[158:159]
	v_rcp_f32_e32 v155, v155
	v_pk_add_f32 v[158:159], v[66:67], v[158:159]
	v_pk_mul_f32 v[150:151], v[150:151], v[144:145]
	v_mul_f32_e32 v196, 0x3d372713, v158
	v_mul_f32_e32 v197, 0x3d372713, v159
	v_mul_f32_e32 v196, v158, v196
	v_mul_f32_e32 v197, v159, v197
	v_fma_f32 v196, v158, v196, v158
	v_fma_f32 v197, v159, v197, v159
	v_mul_f32_e32 v196, 0xc0135761, v196
	v_mul_f32_e32 v197, 0xc0135761, v197
	v_exp_f32_e32 v196, v196
	v_exp_f32_e32 v197, v197
	v_pk_mul_f32 v[144:145], v[152:153], v[154:155]
	v_add_f32_e32 v196, 1.0, v196
	v_add_f32_e32 v197, 1.0, v197
	v_rcp_f32_e32 v196, v196
	v_rcp_f32_e32 v197, v197
	v_pk_mul_f32 v[144:145], v[148:149], v[144:145]
	v_pk_mul_f32 v[148:149], v[158:159], v[196:197]
	s_nop 0
	v_pk_mul_f32 v[148:149], v[146:147], v[148:149]
	v_cvt_pk_bf16_f32 v144, v144, v145
	v_cvt_pk_bf16_f32 v147, v148, v149
	v_mov_b64_e32 v[148:149], s[6:7]
	v_mad_i64_i32 v[148:149], s[48:49], v194, s1, v[148:149]
	v_cvt_pk_bf16_f32 v145, v150, v151
	v_cvt_pk_bf16_f32 v146, v156, v157
	v_lshl_add_u64 v[148:149], v[170:171], 1, v[148:149]
	global_store_dwordx4 v[148:149], v[144:147], off sc1
.LBB0_1086:
	s_or_b64 exec, exec, s[52:53]
	v_add_u32_e32 v194, s73, v174
	v_mov_b32_dpp v149, v140 row_ror:1 row_mask:0xf bank_mask:0xf
	v_mov_b32_dpp v148, v124 row_ror:15 row_mask:0xf bank_mask:0xf
	v_mov_b32_dpp v146, v141 row_ror:1 row_mask:0xf bank_mask:0xf
	v_mov_b32_dpp v144, v125 row_ror:15 row_mask:0xf bank_mask:0xf
	v_mov_b32_dpp v153, v142 row_ror:1 row_mask:0xf bank_mask:0xf
	v_mov_b32_dpp v152, v126 row_ror:15 row_mask:0xf bank_mask:0xf
	v_mov_b32_dpp v151, v143 row_ror:1 row_mask:0xf bank_mask:0xf
	v_mov_b32_dpp v150, v127 row_ror:15 row_mask:0xf bank_mask:0xf
	v_mov_b32_dpp v157, v136 row_ror:1 row_mask:0xf bank_mask:0xf
	v_mov_b32_dpp v156, v120 row_ror:15 row_mask:0xf bank_mask:0xf
	v_mov_b32_dpp v155, v137 row_ror:1 row_mask:0xf bank_mask:0xf
	v_mov_b32_dpp v154, v121 row_ror:15 row_mask:0xf bank_mask:0xf
	v_mov_b32_dpp v159, v138 row_ror:1 row_mask:0xf bank_mask:0xf
	v_mov_b32_dpp v158, v122 row_ror:15 row_mask:0xf bank_mask:0xf
	v_mov_b32_dpp v147, v139 row_ror:1 row_mask:0xf bank_mask:0xf
	v_mov_b32_dpp v145, v123 row_ror:15 row_mask:0xf bank_mask:0xf
	v_cmp_gt_i32_e32 vcc, s86, v194
	s_and_saveexec_b64 s[80:81], vcc
	s_cbranch_execz .LBB0_1088
	v_and_b32_e32 v200, 0x1fff, v194
	v_and_b32_e32 v201, 0xff, v194
	v_cmp_gt_i32_e64 s[48:49], s97, v194
	v_cndmask_b32_e64 v195, v159, v195, s[38:39]
	v_mov_b32_e32 v198, v138
	v_cndmask_b32_e64 v196, v201, v200, s[48:49]
	v_cmp_eq_u32_e32 vcc, 0, v196
	s_waitcnt vmcnt(0)
	v_mov_b32_e32 v199, v58
	v_mov_b32_e32 v196, v70
	v_cndmask_b32_e64 v197, v195, 0, vcc
	v_cmp_eq_u32_e64 s[52:53], s78, v200
	v_pk_mul_f32 v[196:197], v[198:199], v[196:197]
	v_cndmask_b32_e64 v193, v193, v158, s[40:41]
	v_cndmask_b32_e64 v195, 0, 1, s[52:53]
	v_cmp_eq_u32_e64 s[52:53], s12, v201
	v_add_f32_e32 v138, v196, v197
	v_cndmask_b32_e64 v192, v157, v192, s[38:39]
	v_cndmask_b32_e64 v196, 0, 1, s[52:53]
	v_cndmask_b32_e64 v195, v196, v195, s[48:49]
	v_and_b32_e32 v195, 1, v195
	v_cmp_eq_u32_e64 s[48:49], 1, v195
	v_mov_b32_e32 v196, v136
	v_mov_b32_e32 v197, v56
	v_cndmask_b32_e64 v193, v193, 0, s[48:49]
	v_fmac_f32_e32 v138, v62, v193
	v_add_f32_e32 v138, v66, v138
	v_mul_f32_e32 v193, 0x3d372713, v138
	v_mul_f32_e32 v193, v138, v193
	v_fma_f32 v193, v138, v193, v138
	v_mul_f32_e32 v193, 0xc0135761, v193
	v_exp_f32_e32 v195, v193
	v_cndmask_b32_e64 v193, v192, 0, vcc
	v_mov_b32_e32 v192, v68
	v_pk_mul_f32 v[192:193], v[196:197], v[192:193]
	v_cndmask_b32_e64 v191, v191, v156, s[40:41]
	v_add_f32_e32 v136, v192, v193
	v_cndmask_b32_e64 v191, v191, 0, s[48:49]
	v_fmac_f32_e32 v136, v60, v191
	v_add_f32_e32 v136, v64, v136
	v_mul_f32_e32 v191, 0x3d372713, v136
	v_mul_f32_e32 v191, v136, v191
	v_fma_f32 v191, v136, v191, v136
	v_mul_f32_e32 v191, 0xc0135761, v191
	v_exp_f32_e32 v191, v191
	v_add_f32_e32 v192, 1.0, v195
	v_rcp_f32_e32 v192, v192
	v_add_f32_e32 v191, 1.0, v191
	v_rcp_f32_e32 v191, v191
	v_mul_f32_e32 v138, v138, v192
	v_mul_f32_e32 v138, v130, v138
	v_mul_f32_e32 v130, v136, v191
	v_cndmask_b32_e64 v136, v155, v190, s[38:39]
	v_cndmask_b32_e64 v191, v136, 0, vcc
	v_mov_b32_e32 v136, v137
	v_mov_b32_e32 v137, v57
	v_mov_b32_e32 v190, v69
	v_pk_mul_f32 v[136:137], v[136:137], v[190:191]
	v_mul_f32_e32 v130, v128, v130
	v_add_f32_e32 v136, v136, v137
	v_cndmask_b32_e64 v137, v189, v154, s[40:41]
	v_cndmask_b32_e64 v137, v137, 0, s[48:49]
	v_fmac_f32_e32 v136, v61, v137
	v_add_f32_e32 v190, v65, v136
	v_mul_f32_e32 v136, 0x3d372713, v190
	v_mul_f32_e32 v136, v190, v136
	v_fma_f32 v136, v190, v136, v190
	v_mul_f32_e32 v136, 0xc0135761, v136
	v_exp_f32_e32 v191, v136
	v_cndmask_b32_e64 v136, v153, v188, s[38:39]
	v_cndmask_b32_e64 v137, v136, 0, vcc
	v_mov_b32_e32 v188, v142
	v_mov_b32_e32 v189, v78
	v_mov_b32_e32 v136, v94
	v_pk_mul_f32 v[136:137], v[188:189], v[136:137]
	v_mov_b32_e32 v142, v143
	v_add_f32_e32 v136, v136, v137
; __device__ __forceinline__ unsigned pk2(float lo, float hi) { const f32x2_cv v = {lo, hi}; const bf16x2_cv b = __builtin_convertvector(v, bf16x2_cv); return __builtin_bit_cast(unsigned, b); }
; __device__ __forceinline__ float dpp_ror1(float v) { return __builtin_bit_cast(float, __builtin_amdgcn_update_dpp(0, __builtin_bit_cast(int, v), 0x121, 0xF, 0xF, false)); }
; __device__ __forceinline__ float dpp_rol1(float v) { return __builtin_bit_cast(float, __builtin_amdgcn_update_dpp(0, __builtin_bit_cast(int, v), 0x12F, 0xF, 0xF, false)); }
;     __device__ __forceinline__ void operator()(const pg8::f32x4 (&acc)[2][2][4][2], const pg8::Unit& u, int wr, int wc, int fr, int fq) const {
;     ...
;                 for (int c = 0; c < 8; ++c) {
;                     const int n = c >> 2, e = c & 3;
;                     const float x0 = acc[ai][0][m][n][e];
;                     const float ruC = dpp_ror1(x0), rdN = m < 3 ? dpp_rol1(acc[ai][0][m < 3 ? m + 1 : 3][n][e]) : 0.f;
;                     float xu = fr == 0 ? ruP[c] : ruC, xd = fr == 15 ? rdN : rdC[c];
;                     xu = first ? 0.f : xu; xd = last ? 0.f : xd;
;                     ruP[c] = ruC; rdC[c] = rdN;
;                     const float x = w0[c] * xu + w1[c] * x0 + w2[c] * xd + bb[c];
;                     const float u2 = -2.302208198f * (x + 0.044715f * x * x * x);
;                     res[c] = x * __builtin_amdgcn_rcpf(1.0f + __builtin_amdgcn_exp2f(u2)) * acc[ai][1][m][n][e];
;                 }
;                 if (rl >= 1 && rl <= 62 && gr < nrows) { v4u o; o.x = pk2(res[0], res[1]); o.y = pk2(res[2], res[3]); o.z = pk2(res[4], res[5]); o.w = pk2(res[6], res[7]);
;                     *(v4u*)(G + (size_t)gr * DFF + ch0) = o; }
	v_cndmask_b32_e64 v137, v187, v152, s[40:41]
	v_cndmask_b32_e64 v137, v137, 0, s[48:49]
	v_fmac_f32_e32 v136, v82, v137
	v_add_f32_e32 v187, v86, v136
	v_mul_f32_e32 v136, 0x3d372713, v187
	v_mul_f32_e32 v136, v187, v136
	v_fma_f32 v136, v187, v136, v187
	v_mul_f32_e32 v136, 0xc0135761, v136
	v_exp_f32_e32 v136, v136
	v_mov_b32_e32 v143, v79
	v_add_f32_e32 v128, 1.0, v191
	v_rcp_f32_e32 v128, v128
	v_add_f32_e32 v136, 1.0, v136
	v_rcp_f32_e32 v188, v136
	v_cndmask_b32_e64 v136, v151, v186, s[38:39]
	v_cndmask_b32_e64 v137, v136, 0, vcc
	v_mov_b32_e32 v136, v95
	v_pk_mul_f32 v[136:137], v[142:143], v[136:137]
	v_mul_f32_e32 v128, v190, v128
	v_add_f32_e32 v136, v136, v137
	v_cndmask_b32_e64 v137, v185, v150, s[40:41]
	v_cndmask_b32_e64 v137, v137, 0, s[48:49]
	v_fmac_f32_e32 v136, v83, v137
	v_add_f32_e32 v142, v87, v136
	v_mul_f32_e32 v136, 0x3d372713, v142
	v_mul_f32_e32 v136, v142, v136
	v_fma_f32 v136, v142, v136, v142
	v_mul_f32_e32 v136, 0xc0135761, v136
	v_exp_f32_e32 v136, v136
	v_mul_f32_e32 v143, v129, v128
	v_mov_b32_e32 v137, v76
	v_mul_f32_e32 v185, v187, v188
	v_add_f32_e32 v128, 1.0, v136
	v_rcp_f32_e32 v186, v128
	v_cndmask_b32_e64 v128, v149, v184, s[38:39]
	v_cndmask_b32_e64 v129, v128, 0, vcc
	v_mov_b32_e32 v136, v140
	v_mov_b32_e32 v128, v92
	v_pk_mul_f32 v[128:129], v[136:137], v[128:129]
	v_mul_f32_e32 v137, v134, v185
	v_add_f32_e32 v128, v128, v129
	v_cndmask_b32_e64 v129, v183, v148, s[40:41]
	v_cndmask_b32_e64 v129, v129, 0, s[48:49]
	v_fmac_f32_e32 v128, v80, v129
	v_add_f32_e32 v136, v84, v128
	v_mul_f32_e32 v128, 0x3d372713, v136
	v_mul_f32_e32 v128, v136, v128
	v_fma_f32 v128, v136, v128, v136
	v_mul_f32_e32 v128, 0xc0135761, v128
	v_exp_f32_e32 v128, v128
	v_mul_f32_e32 v129, v142, v186
	v_mul_f32_e32 v140, v135, v129
	v_mov_b32_e32 v134, v141
	v_add_f32_e32 v128, 1.0, v128
	v_rcp_f32_e32 v142, v128
	v_cndmask_b32_e64 v128, v146, v181, s[38:39]
	v_cndmask_b32_e64 v129, v128, 0, vcc
	v_mov_b32_e32 v135, v77
	v_mov_b32_e32 v128, v93
	v_pk_mul_f32 v[128:129], v[134:135], v[128:129]
	v_mov_b32_e32 v134, v139
	v_add_f32_e32 v128, v128, v129
	v_cndmask_b32_e64 v129, v179, v144, s[40:41]
	v_cndmask_b32_e64 v129, v129, 0, s[48:49]
	v_fmac_f32_e32 v128, v81, v129
	v_add_f32_e32 v141, v85, v128
	v_mul_f32_e32 v128, 0x3d372713, v141
	v_mul_f32_e32 v128, v141, v128
	v_fma_f32 v128, v141, v128, v141
	v_mul_f32_e32 v128, 0xc0135761, v128
	v_exp_f32_e32 v179, v128
	v_cndmask_b32_e64 v128, v147, v182, s[38:39]
	v_cndmask_b32_e64 v129, v128, 0, vcc
	v_mov_b32_e32 v135, v59
	v_mov_b32_e32 v128, v71
	v_pk_mul_f32 v[128:129], v[134:135], v[128:129]
	v_add_f32_e32 v135, 1.0, v179
	v_add_f32_e32 v128, v128, v129
	v_cndmask_b32_e64 v129, v180, v145, s[40:41]
	v_cndmask_b32_e64 v129, v129, 0, s[48:49]
	v_fmac_f32_e32 v128, v63, v129
	v_add_f32_e32 v128, v67, v128
	v_mul_f32_e32 v129, 0x3d372713, v128
	v_mul_f32_e32 v129, v128, v129
	v_fma_f32 v129, v128, v129, v128
	v_mul_f32_e32 v129, 0xc0135761, v129
	v_exp_f32_e32 v129, v129
	v_rcp_f32_e32 v135, v135
	v_mul_f32_e32 v134, v136, v142
	v_mul_f32_e32 v132, v132, v134
	v_add_f32_e32 v129, 1.0, v129
	v_rcp_f32_e32 v129, v129
	v_mul_f32_e32 v134, v141, v135
	v_mul_f32_e32 v133, v133, v134
	v_cvt_pk_bf16_f32 v130, v130, v143
	v_mul_f32_e32 v128, v128, v129
	v_mul_f32_e32 v131, v131, v128
	v_cvt_pk_bf16_f32 v128, v132, v133
	v_mov_b64_e32 v[132:133], s[6:7]
	v_mad_i64_i32 v[132:133], s[48:49], v194, s1, v[132:133]
	v_cvt_pk_bf16_f32 v129, v137, v140
	v_cvt_pk_bf16_f32 v131, v138, v131
	v_lshl_add_u64 v[132:133], v[170:171], 1, v[132:133]
	global_store_dwordx4 v[132:133], v[128:131], off sc1
.LBB0_1088:
	s_or_b64 exec, exec, s[80:81]
	v_add_u32_e32 v179, s73, v175
	v_mov_b32_dpp v142, v124 row_ror:1 row_mask:0xf bank_mask:0xf
	v_mov_b32_dpp v140, v108 row_ror:15 row_mask:0xf bank_mask:0xf
	v_mov_b32_dpp v143, v125 row_ror:1 row_mask:0xf bank_mask:0xf
	v_mov_b32_dpp v141, v109 row_ror:15 row_mask:0xf bank_mask:0xf
	v_mov_b32_dpp v138, v126 row_ror:1 row_mask:0xf bank_mask:0xf
	v_mov_b32_dpp v136, v110 row_ror:15 row_mask:0xf bank_mask:0xf
	v_mov_b32_dpp v139, v127 row_ror:1 row_mask:0xf bank_mask:0xf
	v_mov_b32_dpp v137, v111 row_ror:15 row_mask:0xf bank_mask:0xf
	v_mov_b32_dpp v134, v120 row_ror:1 row_mask:0xf bank_mask:0xf
	v_mov_b32_dpp v132, v104 row_ror:15 row_mask:0xf bank_mask:0xf
	v_mov_b32_dpp v135, v121 row_ror:1 row_mask:0xf bank_mask:0xf
	v_mov_b32_dpp v133, v105 row_ror:15 row_mask:0xf bank_mask:0xf
	v_mov_b32_dpp v130, v122 row_ror:1 row_mask:0xf bank_mask:0xf
	v_mov_b32_dpp v128, v106 row_ror:15 row_mask:0xf bank_mask:0xf
	v_mov_b32_dpp v131, v123 row_ror:1 row_mask:0xf bank_mask:0xf
	v_mov_b32_dpp v129, v107 row_ror:15 row_mask:0xf bank_mask:0xf
	v_cmp_gt_i32_e32 vcc, s86, v179
	s_and_saveexec_b64 s[80:81], vcc
	v_readlane_b32 s79, v254, 48
	v_readlane_b32 s83, v254, 49
	s_cbranch_execz .LBB0_1090
; __device__ __forceinline__ unsigned pk2(float lo, float hi) { const f32x2_cv v = {lo, hi}; const bf16x2_cv b = __builtin_convertvector(v, bf16x2_cv); return __builtin_bit_cast(unsigned, b); }
; __device__ __forceinline__ float dpp_ror1(float v) { return __builtin_bit_cast(float, __builtin_amdgcn_update_dpp(0, __builtin_bit_cast(int, v), 0x121, 0xF, 0xF, false)); }
; __device__ __forceinline__ float dpp_rol1(float v) { return __builtin_bit_cast(float, __builtin_amdgcn_update_dpp(0, __builtin_bit_cast(int, v), 0x12F, 0xF, 0xF, false)); }
;     __device__ __forceinline__ void operator()(const pg8::f32x4 (&acc)[2][2][4][2], const pg8::Unit& u, int wr, int wc, int fr, int fq) const {
;     ...
;             for (int m = 0; m < 4; ++m) {
;                 const int rl = 16 * m + fr, gr = 62 * kb - 1 + rl;
;                 bool first, last; if (gr < ML) { const int t = gr & 8191; first = t == 0; last = t == 8191; } else { const int t = (gr - ML) & 255; first = t == 0; last = t == 255; }
;                 float res[8];
; #pragma unroll
;                 for (int c = 0; c < 8; ++c) {
;                     const int n = c >> 2, e = c & 3;
;                     const float x0 = acc[ai][0][m][n][e];
;                     const float ruC = dpp_ror1(x0), rdN = m < 3 ? dpp_rol1(acc[ai][0][m < 3 ? m + 1 : 3][n][e]) : 0.f;
;                     float xu = fr == 0 ? ruP[c] : ruC, xd = fr == 15 ? rdN : rdC[c];
;                     xu = first ? 0.f : xu; xd = last ? 0.f : xd;
;                     ruP[c] = ruC; rdC[c] = rdN;
;                     const float x = w0[c] * xu + w1[c] * x0 + w2[c] * xd + bb[c];
;                     const float u2 = -2.302208198f * (x + 0.044715f * x * x * x);
;                     res[c] = x * __builtin_amdgcn_rcpf(1.0f + __builtin_amdgcn_exp2f(u2)) * acc[ai][1][m][n][e];
;                 }
;                 if (rl >= 1 && rl <= 62 && gr < nrows) { v4u o; o.x = pk2(res[0], res[1]); o.y = pk2(res[2], res[3]); o.z = pk2(res[4], res[5]); o.w = pk2(res[6], res[7]);
;                     *(v4u*)(G + (size_t)gr * DFF + ch0) = o; }
	v_and_b32_e32 v184, 0x1fff, v179
	v_and_b32_e32 v185, 0xff, v179
	v_cmp_gt_i32_e64 s[48:49], s97, v179
	v_cndmask_b32_e64 v159, v130, v159, s[38:39]
	v_mov_b32_e32 v182, v122
	v_cndmask_b32_e64 v180, v185, v184, s[48:49]
	v_cmp_eq_u32_e32 vcc, 0, v180
	s_waitcnt vmcnt(0)
	v_mov_b32_e32 v183, v58
	v_mov_b32_e32 v180, v70
	v_cndmask_b32_e64 v181, v159, 0, vcc
	v_cmp_eq_u32_e64 s[52:53], s78, v184
	v_pk_mul_f32 v[180:181], v[182:183], v[180:181]
	v_cndmask_b32_e64 v158, v158, v128, s[40:41]
	v_cndmask_b32_e64 v159, 0, 1, s[52:53]
	v_cmp_eq_u32_e64 s[52:53], s12, v185
	v_add_f32_e32 v122, v180, v181
	v_cndmask_b32_e64 v157, v134, v157, s[38:39]
	v_cndmask_b32_e64 v180, 0, 1, s[52:53]
	v_cndmask_b32_e64 v159, v180, v159, s[48:49]
	v_and_b32_e32 v159, 1, v159
	v_cmp_eq_u32_e64 s[48:49], 1, v159
	v_cndmask_b32_e64 v159, v157, 0, vcc
	v_mov_b32_e32 v180, v120
	v_cndmask_b32_e64 v158, v158, 0, s[48:49]
	v_fmac_f32_e32 v122, v62, v158
	v_add_f32_e32 v122, v66, v122
	v_mul_f32_e32 v158, 0x3d372713, v122
	v_mul_f32_e32 v158, v122, v158
	v_fma_f32 v158, v122, v158, v122
	v_mul_f32_e32 v158, 0xc0135761, v158
	v_exp_f32_e32 v182, v158
	v_mov_b32_e32 v181, v56
	v_mov_b32_e32 v158, v68
	v_pk_mul_f32 v[158:159], v[180:181], v[158:159]
	v_cndmask_b32_e64 v156, v156, v132, s[40:41]
	v_add_f32_e32 v120, v158, v159
	v_cndmask_b32_e64 v156, v156, 0, s[48:49]
	v_fmac_f32_e32 v120, v60, v156
	v_add_f32_e32 v120, v64, v120
	v_mul_f32_e32 v156, 0x3d372713, v120
	v_mul_f32_e32 v156, v120, v156
	v_fma_f32 v156, v120, v156, v120
	v_mul_f32_e32 v156, 0xc0135761, v156
	v_exp_f32_e32 v156, v156
	v_add_f32_e32 v157, 1.0, v182
	v_rcp_f32_e32 v157, v157
	v_add_f32_e32 v156, 1.0, v156
	v_rcp_f32_e32 v156, v156
	v_mul_f32_e32 v122, v122, v157
	v_mul_f32_e32 v122, v114, v122
	v_mul_f32_e32 v114, v120, v156
	v_cndmask_b32_e64 v120, v135, v155, s[38:39]
	v_cndmask_b32_e64 v157, v120, 0, vcc
	v_mov_b32_e32 v120, v121
	v_mov_b32_e32 v121, v57
	v_mov_b32_e32 v156, v69
	v_pk_mul_f32 v[120:121], v[120:121], v[156:157]
	v_mov_b32_e32 v155, v78
	v_add_f32_e32 v120, v120, v121
	v_cndmask_b32_e64 v121, v154, v133, s[40:41]
	v_cndmask_b32_e64 v121, v121, 0, s[48:49]
	v_fmac_f32_e32 v120, v61, v121
	v_add_f32_e32 v156, v65, v120
	v_mul_f32_e32 v120, 0x3d372713, v156
	v_mul_f32_e32 v120, v156, v120
	v_fma_f32 v120, v156, v120, v156
	v_mul_f32_e32 v120, 0xc0135761, v120
	v_exp_f32_e32 v157, v120
	v_cndmask_b32_e64 v120, v138, v153, s[38:39]
	v_cndmask_b32_e64 v121, v120, 0, vcc
	v_mov_b32_e32 v154, v126
	v_mov_b32_e32 v120, v94
	v_pk_mul_f32 v[120:121], v[154:155], v[120:121]
	v_mov_b32_e32 v126, v127
	v_add_f32_e32 v120, v120, v121
	v_cndmask_b32_e64 v121, v152, v136, s[40:41]
	v_cndmask_b32_e64 v121, v121, 0, s[48:49]
	v_fmac_f32_e32 v120, v82, v121
	v_add_f32_e32 v152, v86, v120
	v_mul_f32_e32 v120, 0x3d372713, v152
	v_mul_f32_e32 v120, v152, v120
	v_fma_f32 v120, v152, v120, v152
	v_mul_f32_e32 v120, 0xc0135761, v120
	v_exp_f32_e32 v120, v120
	v_mov_b32_e32 v127, v79
	v_mul_f32_e32 v114, v112, v114
	v_add_f32_e32 v112, 1.0, v157
	v_add_f32_e32 v120, 1.0, v120
	v_rcp_f32_e32 v153, v120
	v_cndmask_b32_e64 v120, v139, v151, s[38:39]
	v_cndmask_b32_e64 v121, v120, 0, vcc
	v_mov_b32_e32 v120, v95
	v_pk_mul_f32 v[120:121], v[126:127], v[120:121]
	v_rcp_f32_e32 v112, v112
	v_add_f32_e32 v120, v120, v121
	v_cndmask_b32_e64 v121, v150, v137, s[40:41]
	v_cndmask_b32_e64 v121, v121, 0, s[48:49]
	v_fmac_f32_e32 v120, v83, v121
	v_add_f32_e32 v126, v87, v120
	v_mul_f32_e32 v120, 0x3d372713, v126
	v_mul_f32_e32 v120, v126, v120
	v_fma_f32 v120, v126, v120, v126
	v_mul_f32_e32 v120, 0xc0135761, v120
	v_exp_f32_e32 v120, v120
	v_mul_f32_e32 v112, v156, v112
	v_mul_f32_e32 v127, v113, v112
	v_mov_b32_e32 v121, v76
	v_add_f32_e32 v112, 1.0, v120
	v_rcp_f32_e32 v151, v112
	v_cndmask_b32_e64 v112, v142, v149, s[38:39]
	v_cndmask_b32_e64 v113, v112, 0, vcc
	v_mov_b32_e32 v120, v124
	v_mov_b32_e32 v112, v92
	v_pk_mul_f32 v[112:113], v[120:121], v[112:113]
	v_mul_f32_e32 v150, v152, v153
	v_add_f32_e32 v112, v112, v113
	v_cndmask_b32_e64 v113, v148, v140, s[40:41]
	v_cndmask_b32_e64 v113, v113, 0, s[48:49]
	v_fmac_f32_e32 v112, v80, v113
	v_add_f32_e32 v120, v84, v112
	v_mul_f32_e32 v112, 0x3d372713, v120
	v_mul_f32_e32 v112, v120, v112
	v_fma_f32 v112, v120, v112, v120
	v_mul_f32_e32 v112, 0xc0135761, v112
	v_exp_f32_e32 v112, v112
	v_mul_f32_e32 v113, v126, v151
	v_mul_f32_e32 v121, v118, v150
	v_mul_f32_e32 v124, v119, v113
	v_add_f32_e32 v112, 1.0, v112
	v_rcp_f32_e32 v126, v112
	v_cndmask_b32_e64 v112, v143, v146, s[38:39]
	v_cndmask_b32_e64 v113, v112, 0, vcc
	v_mov_b32_e32 v118, v125
	v_mov_b32_e32 v119, v77
	v_mov_b32_e32 v112, v93
	v_pk_mul_f32 v[112:113], v[118:119], v[112:113]
	v_mov_b32_e32 v118, v123
	v_add_f32_e32 v112, v112, v113
	v_cndmask_b32_e64 v113, v144, v141, s[40:41]
	v_cndmask_b32_e64 v113, v113, 0, s[48:49]
	v_fmac_f32_e32 v112, v81, v113
	v_add_f32_e32 v125, v85, v112
	v_mul_f32_e32 v112, 0x3d372713, v125
	v_mul_f32_e32 v112, v125, v112
	v_fma_f32 v112, v125, v112, v125
	v_mul_f32_e32 v112, 0xc0135761, v112
	v_exp_f32_e32 v144, v112
	v_cndmask_b32_e64 v112, v131, v147, s[38:39]
	v_cndmask_b32_e64 v113, v112, 0, vcc
	v_mov_b32_e32 v119, v59
	v_mov_b32_e32 v112, v71
	v_pk_mul_f32 v[112:113], v[118:119], v[112:113]
	v_add_f32_e32 v119, 1.0, v144
	v_add_f32_e32 v112, v112, v113
	v_cndmask_b32_e64 v113, v145, v129, s[40:41]
	v_cndmask_b32_e64 v113, v113, 0, s[48:49]
	v_fmac_f32_e32 v112, v63, v113
	v_add_f32_e32 v112, v67, v112
	v_mul_f32_e32 v113, 0x3d372713, v112
	v_mul_f32_e32 v113, v112, v113
	v_fma_f32 v113, v112, v113, v112
	v_mul_f32_e32 v113, 0xc0135761, v113
	v_exp_f32_e32 v113, v113
	v_rcp_f32_e32 v119, v119
	v_mul_f32_e32 v118, v120, v126
	v_mul_f32_e32 v116, v116, v118
	v_add_f32_e32 v113, 1.0, v113
	v_rcp_f32_e32 v113, v113
	v_mul_f32_e32 v118, v125, v119
	v_mul_f32_e32 v117, v117, v118
	v_cvt_pk_bf16_f32 v114, v114, v127
	v_mul_f32_e32 v112, v112, v113
	v_mul_f32_e32 v115, v115, v112
	v_cvt_pk_bf16_f32 v112, v116, v117
	v_mov_b64_e32 v[116:117], s[6:7]
	v_mad_i64_i32 v[116:117], s[48:49], v179, s1, v[116:117]
	v_cvt_pk_bf16_f32 v113, v121, v124
	v_cvt_pk_bf16_f32 v115, v122, v115
	v_lshl_add_u64 v[116:117], v[170:171], 1, v[116:117]
	global_store_dwordx4 v[116:117], v[112:115], off sc1
; __device__ __forceinline__ unsigned pk2(float lo, float hi) { const f32x2_cv v = {lo, hi}; const bf16x2_cv b = __builtin_convertvector(v, bf16x2_cv); return __builtin_bit_cast(unsigned, b); }
; __device__ __forceinline__ float dpp_ror1(float v) { return __builtin_bit_cast(float, __builtin_amdgcn_update_dpp(0, __builtin_bit_cast(int, v), 0x121, 0xF, 0xF, false)); }
; __device__ __forceinline__ float dpp_rol1(float v) { return __builtin_bit_cast(float, __builtin_amdgcn_update_dpp(0, __builtin_bit_cast(int, v), 0x12F, 0xF, 0xF, false)); }
;     __device__ __forceinline__ void operator()(const pg8::f32x4 (&acc)[2][2][4][2], const pg8::Unit& u, int wr, int wc, int fr, int fq) const {
;     ...
;             for (int m = 0; m < 4; ++m) {
;                 const int rl = 16 * m + fr, gr = 62 * kb - 1 + rl;
;                 bool first, last; if (gr < ML) { const int t = gr & 8191; first = t == 0; last = t == 8191; } else { const int t = (gr - ML) & 255; first = t == 0; last = t == 255; }
;                 float res[8];
; #pragma unroll
;                 for (int c = 0; c < 8; ++c) {
;                     const int n = c >> 2, e = c & 3;
;                     const float x0 = acc[ai][0][m][n][e];
;                     const float ruC = dpp_ror1(x0), rdN = m < 3 ? dpp_rol1(acc[ai][0][m < 3 ? m + 1 : 3][n][e]) : 0.f;
;                     float xu = fr == 0 ? ruP[c] : ruC, xd = fr == 15 ? rdN : rdC[c];
;                     xu = first ? 0.f : xu; xd = last ? 0.f : xd;
;                     ruP[c] = ruC; rdC[c] = rdN;
;                     const float x = w0[c] * xu + w1[c] * x0 + w2[c] * xd + bb[c];
;                     const float u2 = -2.302208198f * (x + 0.044715f * x * x * x);
;                     res[c] = x * __builtin_amdgcn_rcpf(1.0f + __builtin_amdgcn_exp2f(u2)) * acc[ai][1][m][n][e];
;                 }
;                 if (rl >= 1 && rl <= 62 && gr < nrows) { v4u o; o.x = pk2(res[0], res[1]); o.y = pk2(res[2], res[3]); o.z = pk2(res[4], res[5]); o.w = pk2(res[6], res[7]);
;                     *(v4u*)(G + (size_t)gr * DFF + ch0) = o; }
.LBB0_1090:
	s_or_b64 exec, exec, s[80:81]
	s_nop 0
	v_add_u32_e32 v112, s73, v176
	v_cmp_gt_i32_e32 vcc, s86, v112
	v_mov_b32_dpp v119, v108 row_ror:1 row_mask:0xf bank_mask:0xf
	v_mov_b32_dpp v120, v109 row_ror:1 row_mask:0xf bank_mask:0xf
	v_mov_b32_dpp v117, v110 row_ror:1 row_mask:0xf bank_mask:0xf
	v_mov_b32_dpp v118, v111 row_ror:1 row_mask:0xf bank_mask:0xf
	v_mov_b32_dpp v115, v104 row_ror:1 row_mask:0xf bank_mask:0xf
	v_mov_b32_dpp v116, v105 row_ror:1 row_mask:0xf bank_mask:0xf
	v_mov_b32_dpp v113, v106 row_ror:1 row_mask:0xf bank_mask:0xf
	v_mov_b32_dpp v114, v107 row_ror:1 row_mask:0xf bank_mask:0xf
	s_and_b64 s[48:49], s[44:45], vcc
	s_and_saveexec_b64 s[52:53], s[48:49]
	s_cbranch_execz .LBB0_1092
	v_and_b32_e32 v121, 0x1fff, v112
	v_and_b32_e32 v122, 0xff, v112
	v_cmp_gt_i32_e32 vcc, s97, v112
	v_cmp_eq_u32_e64 s[48:49], s78, v121
	v_cndmask_b32_e64 v119, v119, v142, s[38:39]
	v_cndmask_b32_e32 v123, v122, v121, vcc
	v_cndmask_b32_e64 v121, 0, 1, s[48:49]
	v_cmp_eq_u32_e64 s[48:49], s12, v122
	v_cndmask_b32_e64 v120, v120, v143, s[38:39]
	s_waitcnt vmcnt(0)
	v_pk_mul_f32 v[108:109], v[108:109], v[92:93]
	v_cndmask_b32_e64 v122, 0, 1, s[48:49]
	v_cndmask_b32_e32 v121, v122, v121, vcc
	v_and_b32_e32 v122, 1, v121
	v_cmp_eq_u32_e64 s[48:49], 0, v123
	v_cmp_eq_u32_e32 vcc, 1, v122
	v_cndmask_b32_e64 v117, v117, v138, s[38:39]
	v_cndmask_b32_e64 v121, v120, 0, s[48:49]
	v_cndmask_b32_e64 v120, v119, 0, s[48:49]
	v_pk_fma_f32 v[108:109], v[76:77], v[120:121], v[108:109]
	v_cndmask_b32_e64 v121, v141, 0, vcc
	v_cndmask_b32_e64 v120, v140, 0, vcc
	v_pk_fma_f32 v[108:109], v[80:81], v[120:121], v[108:109]
	v_cndmask_b32_e64 v118, v118, v139, s[38:39]
	v_pk_add_f32 v[108:109], v[84:85], v[108:109]
	v_pk_mul_f32 v[110:111], v[110:111], v[94:95]
	v_mul_f32_e32 v119, 0x3d372713, v108
	v_mul_f32_e32 v119, v108, v119
	v_fma_f32 v119, v108, v119, v108
	v_mul_f32_e32 v119, 0xc0135761, v119
	v_exp_f32_e32 v119, v119
	v_mul_f32_e32 v120, 0x3d372713, v109
	v_mul_f32_e32 v120, v109, v120
	v_fma_f32 v120, v109, v120, v109
	v_mul_f32_e32 v120, 0xc0135761, v120
	v_add_f32_e32 v119, 1.0, v119
	v_exp_f32_e32 v121, v120
	v_rcp_f32_e32 v120, v119
	v_cndmask_b32_e64 v119, v118, 0, s[48:49]
	v_cndmask_b32_e64 v118, v117, 0, s[48:49]
	v_pk_fma_f32 v[110:111], v[78:79], v[118:119], v[110:111]
	v_cndmask_b32_e64 v119, v137, 0, vcc
	v_cndmask_b32_e64 v118, v136, 0, vcc
	v_pk_fma_f32 v[110:111], v[82:83], v[118:119], v[110:111]
	v_add_f32_e32 v121, 1.0, v121
	v_pk_add_f32 v[110:111], v[86:87], v[110:111]
	v_rcp_f32_e32 v121, v121
	v_mul_f32_e32 v117, 0x3d372713, v110
	v_mul_f32_e32 v117, v110, v117
	v_mul_f32_e32 v118, 0x3d372713, v111
	v_fma_f32 v117, v110, v117, v110
	v_mul_f32_e32 v118, v111, v118
	v_mul_f32_e32 v117, 0xc0135761, v117
	v_fma_f32 v118, v111, v118, v111
	v_exp_f32_e32 v117, v117
	v_mul_f32_e32 v118, 0xc0135761, v118
	v_exp_f32_e32 v119, v118
	v_pk_mul_f32 v[108:109], v[108:109], v[120:121]
	v_add_f32_e32 v117, 1.0, v117
	v_rcp_f32_e32 v118, v117
	v_add_f32_e32 v117, 1.0, v119
	v_rcp_f32_e32 v119, v117
	v_pk_mul_f32 v[100:101], v[100:101], v[108:109]
	v_cndmask_b32_e64 v113, v113, v130, s[38:39]
	v_cndmask_b32_e64 v114, v114, v131, s[38:39]
	v_pk_mul_f32 v[108:109], v[110:111], v[118:119]
	v_cndmask_b32_e64 v110, v115, v134, s[38:39]
	v_cndmask_b32_e64 v111, v116, v135, s[38:39]
	v_pk_mul_f32 v[104:105], v[104:105], v[68:69]
	v_cndmask_b32_e64 v111, v111, 0, s[48:49]
	v_cndmask_b32_e64 v110, v110, 0, s[48:49]
	v_pk_mul_f32 v[106:107], v[106:107], v[70:71]
	v_cndmask_b32_e64 v115, v114, 0, s[48:49]
	v_cndmask_b32_e64 v114, v113, 0, s[48:49]
	v_pk_fma_f32 v[104:105], v[56:57], v[110:111], v[104:105]
	v_cndmask_b32_e64 v111, v133, 0, vcc
	v_cndmask_b32_e64 v110, v132, 0, vcc
	v_pk_fma_f32 v[106:107], v[58:59], v[114:115], v[106:107]
	v_cndmask_b32_e64 v115, v129, 0, vcc
	v_cndmask_b32_e64 v114, v128, 0, vcc
	v_pk_fma_f32 v[104:105], v[60:61], v[110:111], v[104:105]
	v_pk_fma_f32 v[106:107], v[62:63], v[114:115], v[106:107]
	v_pk_add_f32 v[104:105], v[64:65], v[104:105]
	v_pk_add_f32 v[106:107], v[66:67], v[106:107]
	v_mul_f32_e32 v110, 0x3d372713, v104
	v_mul_f32_e32 v111, 0x3d372713, v105
	v_mul_f32_e32 v113, 0x3d372713, v106
	v_mul_f32_e32 v110, v104, v110
	v_mul_f32_e32 v111, v105, v111
	v_mul_f32_e32 v113, v106, v113
	v_mul_f32_e32 v114, 0x3d372713, v107
	v_fma_f32 v110, v104, v110, v104
	v_fma_f32 v111, v105, v111, v105
	v_fma_f32 v113, v106, v113, v106
	v_mul_f32_e32 v114, v107, v114
	v_mul_f32_e32 v110, 0xc0135761, v110
	v_mul_f32_e32 v111, 0xc0135761, v111
	v_mul_f32_e32 v113, 0xc0135761, v113
	v_fma_f32 v114, v107, v114, v107
	v_exp_f32_e32 v110, v110
	v_exp_f32_e32 v111, v111
	v_exp_f32_e32 v113, v113
	v_mul_f32_e32 v114, 0xc0135761, v114
	v_exp_f32_e32 v115, v114
	v_add_f32_e32 v110, 1.0, v110
	v_add_f32_e32 v111, 1.0, v111
	v_add_f32_e32 v113, 1.0, v113
	v_rcp_f32_e32 v110, v110
	v_rcp_f32_e32 v111, v111
	v_rcp_f32_e32 v114, v113
	v_add_f32_e32 v113, 1.0, v115
	v_rcp_f32_e32 v115, v113
	v_pk_mul_f32 v[104:105], v[104:105], v[110:111]
	v_pk_mul_f32 v[102:103], v[102:103], v[108:109]
	v_pk_mul_f32 v[104:105], v[96:97], v[104:105]
	v_pk_mul_f32 v[96:97], v[106:107], v[114:115]
	s_nop 0
	v_pk_mul_f32 v[106:107], v[98:99], v[96:97]
	v_cvt_pk_bf16_f32 v96, v100, v101
	v_mov_b64_e32 v[100:101], s[6:7]
	v_mad_i64_i32 v[100:101], s[48:49], v112, s1, v[100:101]
	v_cvt_pk_bf16_f32 v97, v102, v103
	v_cvt_pk_bf16_f32 v98, v104, v105
	v_cvt_pk_bf16_f32 v99, v106, v107
	v_lshl_add_u64 v[100:101], v[170:171], 1, v[100:101]
	global_store_dwordx4 v[100:101], v[96:99], off sc1
; __device__ __forceinline__ unsigned pk2(float lo, float hi) { const f32x2_cv v = {lo, hi}; const bf16x2_cv b = __builtin_convertvector(v, bf16x2_cv); return __builtin_bit_cast(unsigned, b); }
; __device__ __forceinline__ float dpp_ror1(float v) { return __builtin_bit_cast(float, __builtin_amdgcn_update_dpp(0, __builtin_bit_cast(int, v), 0x121, 0xF, 0xF, false)); }
; __device__ __forceinline__ float dpp_rol1(float v) { return __builtin_bit_cast(float, __builtin_amdgcn_update_dpp(0, __builtin_bit_cast(int, v), 0x12F, 0xF, 0xF, false)); }
;     __device__ __forceinline__ void operator()(const pg8::f32x4 (&acc)[2][2][4][2], const pg8::Unit& u, int wr, int wc, int fr, int fq) const {
;     ...
;         for (int ai = 0; ai < 2; ++ai) {
;             const int kb = u.pm * 4 + ai * 2 + wr;
;             float ruP[8], rdC[8];
; #pragma unroll
;             for (int c = 0; c < 8; ++c) { ruP[c] = 0.f; rdC[c] = dpp_rol1(acc[ai][0][0][c >> 2][c & 3]); }
; #pragma unroll
;             for (int m = 0; m < 4; ++m) {
;                 const int rl = 16 * m + fr, gr = 62 * kb - 1 + rl;
;                 bool first, last; if (gr < ML) { const int t = gr & 8191; first = t == 0; last = t == 8191; } else { const int t = (gr - ML) & 255; first = t == 0; last = t == 255; }
;                 float res[8];
; #pragma unroll
;                 for (int c = 0; c < 8; ++c) {
;                     const int n = c >> 2, e = c & 3;
;                     const float x0 = acc[ai][0][m][n][e];
;                     const float ruC = dpp_ror1(x0), rdN = m < 3 ? dpp_rol1(acc[ai][0][m < 3 ? m + 1 : 3][n][e]) : 0.f;
;                     float xu = fr == 0 ? ruP[c] : ruC, xd = fr == 15 ? rdN : rdC[c];
;                     xu = first ? 0.f : xu; xd = last ? 0.f : xd;
;                     ruP[c] = ruC; rdC[c] = rdN;
;                     const float x = w0[c] * xu + w1[c] * x0 + w2[c] * xd + bb[c];
;                     const float u2 = -2.302208198f * (x + 0.044715f * x * x * x);
;                     res[c] = x * __builtin_amdgcn_rcpf(1.0f + __builtin_amdgcn_exp2f(u2)) * acc[ai][1][m][n][e];
;                 }
;                 if (rl >= 1 && rl <= 62 && gr < nrows) { v4u o; o.x = pk2(res[0], res[1]); o.y = pk2(res[2], res[3]); o.z = pk2(res[4], res[5]); o.w = pk2(res[6], res[7]);
;                     *(v4u*)(G + (size_t)gr * DFF + ch0) = o; }
.LBB0_1092:
	s_or_b64 exec, exec, s[52:53]
	s_addk_i32 s65, 0x7b
	v_add_u32_e32 v111, s65, v172
	v_cmp_gt_i32_e32 vcc, s86, v111
	v_mov_b32_dpp v115, v72 row_ror:15 row_mask:0xf bank_mask:0xf
	v_mov_b32_dpp v116, v73 row_ror:15 row_mask:0xf bank_mask:0xf
	v_mov_b32_dpp v117, v74 row_ror:15 row_mask:0xf bank_mask:0xf
	v_mov_b32_dpp v118, v75 row_ror:15 row_mask:0xf bank_mask:0xf
	v_mov_b32_dpp v119, v88 row_ror:15 row_mask:0xf bank_mask:0xf
	v_mov_b32_dpp v120, v89 row_ror:15 row_mask:0xf bank_mask:0xf
	v_mov_b32_dpp v113, v90 row_ror:15 row_mask:0xf bank_mask:0xf
	v_mov_b32_dpp v114, v91 row_ror:15 row_mask:0xf bank_mask:0xf
	v_mov_b32_dpp v101, v72 row_ror:1 row_mask:0xf bank_mask:0xf
	v_mov_b32_dpp v100, v44 row_ror:15 row_mask:0xf bank_mask:0xf
	v_mov_b32_dpp v98, v73 row_ror:1 row_mask:0xf bank_mask:0xf
	v_mov_b32_dpp v96, v45 row_ror:15 row_mask:0xf bank_mask:0xf
	v_mov_b32_dpp v105, v74 row_ror:1 row_mask:0xf bank_mask:0xf
	v_mov_b32_dpp v104, v46 row_ror:15 row_mask:0xf bank_mask:0xf
	v_mov_b32_dpp v103, v75 row_ror:1 row_mask:0xf bank_mask:0xf
	v_mov_b32_dpp v102, v47 row_ror:15 row_mask:0xf bank_mask:0xf
	v_mov_b32_dpp v109, v88 row_ror:1 row_mask:0xf bank_mask:0xf
	v_mov_b32_dpp v108, v40 row_ror:15 row_mask:0xf bank_mask:0xf
	v_mov_b32_dpp v107, v89 row_ror:1 row_mask:0xf bank_mask:0xf
	v_mov_b32_dpp v106, v41 row_ror:15 row_mask:0xf bank_mask:0xf
	v_mov_b32_dpp v112, v90 row_ror:1 row_mask:0xf bank_mask:0xf
	v_mov_b32_dpp v110, v42 row_ror:15 row_mask:0xf bank_mask:0xf
	v_mov_b32_dpp v99, v91 row_ror:1 row_mask:0xf bank_mask:0xf
	v_mov_b32_dpp v97, v43 row_ror:15 row_mask:0xf bank_mask:0xf
	s_and_b64 s[48:49], s[42:43], vcc
	s_and_saveexec_b64 s[52:53], s[48:49]
	s_cbranch_execz .LBB0_1094
	v_and_b32_e32 v121, 0x1fff, v111
	v_and_b32_e32 v122, 0xff, v111
	v_cmp_gt_i32_e32 vcc, s97, v111
	v_cmp_eq_u32_e64 s[48:49], s78, v121
	s_waitcnt vmcnt(0)
	v_pk_mul_f32 v[88:89], v[88:89], v[68:69]
	v_cndmask_b32_e32 v123, v122, v121, vcc
	v_cndmask_b32_e64 v121, 0, 1, s[48:49]
	v_cmp_eq_u32_e64 s[48:49], s12, v122
	v_cndmask_b32_e64 v119, v119, v108, s[40:41]
	v_cndmask_b32_e64 v120, v120, v106, s[40:41]
	v_cndmask_b32_e64 v122, 0, 1, s[48:49]
	v_cndmask_b32_e32 v121, v122, v121, vcc
	v_and_b32_e32 v121, 1, v121
	v_cmp_eq_u32_e32 vcc, 0, v123
	v_cmp_eq_u32_e64 s[48:49], 1, v121
	v_pk_mul_f32 v[72:73], v[72:73], v[92:93]
	v_cndmask_b32_e64 v123, v107, 0, vcc
	v_cndmask_b32_e64 v122, v109, 0, vcc
	v_pk_fma_f32 v[88:89], v[56:57], v[122:123], v[88:89]
	v_cndmask_b32_e64 v121, v120, 0, s[48:49]
	v_cndmask_b32_e64 v120, v119, 0, s[48:49]
	v_pk_fma_f32 v[88:89], v[60:61], v[120:121], v[88:89]
	v_cndmask_b32_e64 v115, v115, v100, s[40:41]
	v_pk_add_f32 v[88:89], v[64:65], v[88:89]
	v_cndmask_b32_e64 v116, v116, v96, s[40:41]
	v_mul_f32_e32 v119, 0x3d372713, v88
	v_mul_f32_e32 v119, v88, v119
	v_mul_f32_e32 v120, 0x3d372713, v89
	v_fma_f32 v119, v88, v119, v88
	v_mul_f32_e32 v120, v89, v120
	v_mul_f32_e32 v119, 0xc0135761, v119
	v_fma_f32 v120, v89, v120, v89
	v_exp_f32_e32 v119, v119
	v_mul_f32_e32 v120, 0xc0135761, v120
	v_exp_f32_e32 v121, v120
	v_pk_mul_f32 v[90:91], v[90:91], v[70:71]
	v_add_f32_e32 v119, 1.0, v119
	v_rcp_f32_e32 v120, v119
	v_add_f32_e32 v119, 1.0, v121
	v_rcp_f32_e32 v121, v119
	v_cndmask_b32_e64 v119, v98, 0, vcc
	v_cndmask_b32_e64 v113, v113, v110, s[40:41]
	v_cndmask_b32_e64 v114, v114, v97, s[40:41]
	v_pk_mul_f32 v[88:89], v[88:89], v[120:121]
	s_nop 0
	v_pk_mul_f32 v[88:89], v[48:49], v[88:89]
	v_pk_mul_f32 v[48:49], v[74:75], v[94:95]
	v_cndmask_b32_e64 v75, v103, 0, vcc
	v_cndmask_b32_e64 v74, v105, 0, vcc
	v_pk_fma_f32 v[48:49], v[78:79], v[74:75], v[48:49]
	v_cndmask_b32_e64 v74, v117, v104, s[40:41]
	v_cndmask_b32_e64 v75, v118, v102, s[40:41]
	v_cndmask_b32_e64 v75, v75, 0, s[48:49]
	v_cndmask_b32_e64 v74, v74, 0, s[48:49]
	v_pk_fma_f32 v[48:49], v[82:83], v[74:75], v[48:49]
	v_cndmask_b32_e64 v118, v101, 0, vcc
	v_pk_add_f32 v[48:49], v[86:87], v[48:49]
	v_pk_fma_f32 v[72:73], v[76:77], v[118:119], v[72:73]
	v_mul_f32_e32 v74, 0x3d372713, v48
	v_mul_f32_e32 v75, 0x3d372713, v49
	v_mul_f32_e32 v74, v48, v74
	v_mul_f32_e32 v75, v49, v75
	v_fma_f32 v74, v48, v74, v48
	v_fma_f32 v75, v49, v75, v49
	v_cndmask_b32_e64 v117, v116, 0, s[48:49]
	v_cndmask_b32_e64 v116, v115, 0, s[48:49]
	v_mul_f32_e32 v74, 0xc0135761, v74
	v_mul_f32_e32 v75, 0xc0135761, v75
	v_pk_fma_f32 v[72:73], v[80:81], v[116:117], v[72:73]
	v_exp_f32_e32 v74, v74
	v_exp_f32_e32 v75, v75
	v_pk_add_f32 v[72:73], v[84:85], v[72:73]
	v_cndmask_b32_e64 v117, v99, 0, vcc
	v_mul_f32_e32 v116, 0x3d372713, v73
	v_mul_f32_e32 v115, 0x3d372713, v72
	v_mul_f32_e32 v116, v73, v116
	v_mul_f32_e32 v115, v72, v115
	v_fma_f32 v116, v73, v116, v73
	v_add_f32_e32 v74, 1.0, v74
	v_add_f32_e32 v75, 1.0, v75
	v_fma_f32 v115, v72, v115, v72
	v_mul_f32_e32 v116, 0xc0135761, v116
	v_rcp_f32_e32 v74, v74
	v_rcp_f32_e32 v75, v75
	v_mul_f32_e32 v115, 0xc0135761, v115
	v_exp_f32_e32 v116, v116
	v_exp_f32_e32 v115, v115
	v_pk_mul_f32 v[48:49], v[48:49], v[74:75]
	v_add_f32_e32 v75, 1.0, v116
	v_cndmask_b32_e64 v116, v112, 0, vcc
	v_add_f32_e32 v74, 1.0, v115
	v_pk_fma_f32 v[90:91], v[58:59], v[116:117], v[90:91]
	v_cndmask_b32_e64 v115, v114, 0, s[48:49]
	v_cndmask_b32_e64 v114, v113, 0, s[48:49]
	v_pk_fma_f32 v[90:91], v[62:63], v[114:115], v[90:91]
	v_rcp_f32_e32 v74, v74
	v_pk_add_f32 v[90:91], v[66:67], v[90:91]
	v_rcp_f32_e32 v75, v75
	v_mul_f32_e32 v113, 0x3d372713, v90
	v_mul_f32_e32 v113, v90, v113
	v_mul_f32_e32 v114, 0x3d372713, v91
	v_fma_f32 v113, v90, v113, v90
	v_mul_f32_e32 v114, v91, v114
	v_mul_f32_e32 v113, 0xc0135761, v113
	v_fma_f32 v114, v91, v114, v91
	v_exp_f32_e32 v113, v113
	v_mul_f32_e32 v114, 0xc0135761, v114
	v_exp_f32_e32 v115, v114
	v_pk_mul_f32 v[54:55], v[54:55], v[48:49]
	v_add_f32_e32 v113, 1.0, v113
	v_rcp_f32_e32 v114, v113
	v_add_f32_e32 v113, 1.0, v115
	v_rcp_f32_e32 v115, v113
	v_pk_mul_f32 v[48:49], v[72:73], v[74:75]
	s_nop 0
	v_pk_mul_f32 v[48:49], v[52:53], v[48:49]
	v_pk_mul_f32 v[52:53], v[90:91], v[114:115]
	v_cvt_pk_bf16_f32 v48, v48, v49
	v_pk_mul_f32 v[52:53], v[50:51], v[52:53]
	v_cvt_pk_bf16_f32 v49, v54, v55
	v_cvt_pk_bf16_f32 v51, v52, v53
	v_mov_b64_e32 v[52:53], s[6:7]
	v_mad_i64_i32 v[52:53], s[48:49], v111, s1, v[52:53]
	v_cvt_pk_bf16_f32 v50, v88, v89
	v_lshl_add_u64 v[52:53], v[170:171], 1, v[52:53]
	global_store_dwordx4 v[52:53], v[48:51], off sc1
; __device__ __forceinline__ float dpp_ror1(float v) { return __builtin_bit_cast(float, __builtin_amdgcn_update_dpp(0, __builtin_bit_cast(int, v), 0x121, 0xF, 0xF, false)); }
; __device__ __forceinline__ float dpp_rol1(float v) { return __builtin_bit_cast(float, __builtin_amdgcn_update_dpp(0, __builtin_bit_cast(int, v), 0x12F, 0xF, 0xF, false)); }
;     __device__ __forceinline__ void operator()(const pg8::f32x4 (&acc)[2][2][4][2], const pg8::Unit& u, int wr, int wc, int fr, int fq) const {
;     ...
;             for (int m = 0; m < 4; ++m) {
;                 const int rl = 16 * m + fr, gr = 62 * kb - 1 + rl;
;                 bool first, last; if (gr < ML) { const int t = gr & 8191; first = t == 0; last = t == 8191; } else { const int t = (gr - ML) & 255; first = t == 0; last = t == 255; }
;                 float res[8];
; #pragma unroll
;                 for (int c = 0; c < 8; ++c) {
;                     const int n = c >> 2, e = c & 3;
;                     const float x0 = acc[ai][0][m][n][e];
;                     const float ruC = dpp_ror1(x0), rdN = m < 3 ? dpp_rol1(acc[ai][0][m < 3 ? m + 1 : 3][n][e]) : 0.f;
;                     float xu = fr == 0 ? ruP[c] : ruC, xd = fr == 15 ? rdN : rdC[c];
;                     xu = first ? 0.f : xu; xd = last ? 0.f : xd;
;                     ruP[c] = ruC; rdC[c] = rdN;
;                     const float x = w0[c] * xu + w1[c] * x0 + w2[c] * xd + bb[c];
;                     const float u2 = -2.302208198f * (x + 0.044715f * x * x * x);
;                     res[c] = x * __builtin_amdgcn_rcpf(1.0f + __builtin_amdgcn_exp2f(u2)) * acc[ai][1][m][n][e];
.LBB0_1094:
	s_or_b64 exec, exec, s[52:53]
	v_add_u32_e32 v111, s65, v174
	v_mov_b32_dpp v53, v44 row_ror:1 row_mask:0xf bank_mask:0xf
	v_mov_b32_dpp v52, v28 row_ror:15 row_mask:0xf bank_mask:0xf
	v_mov_b32_dpp v50, v45 row_ror:1 row_mask:0xf bank_mask:0xf
	v_mov_b32_dpp v48, v29 row_ror:15 row_mask:0xf bank_mask:0xf
	v_mov_b32_dpp v73, v46 row_ror:1 row_mask:0xf bank_mask:0xf
	v_mov_b32_dpp v72, v30 row_ror:15 row_mask:0xf bank_mask:0xf
	v_mov_b32_dpp v55, v47 row_ror:1 row_mask:0xf bank_mask:0xf
	v_mov_b32_dpp v54, v31 row_ror:15 row_mask:0xf bank_mask:0xf
	v_mov_b32_dpp v89, v40 row_ror:1 row_mask:0xf bank_mask:0xf
	v_mov_b32_dpp v88, v24 row_ror:15 row_mask:0xf bank_mask:0xf
	v_mov_b32_dpp v75, v41 row_ror:1 row_mask:0xf bank_mask:0xf
	v_mov_b32_dpp v74, v25 row_ror:15 row_mask:0xf bank_mask:0xf
	v_mov_b32_dpp v91, v42 row_ror:1 row_mask:0xf bank_mask:0xf
	v_mov_b32_dpp v90, v26 row_ror:15 row_mask:0xf bank_mask:0xf
	v_mov_b32_dpp v51, v43 row_ror:1 row_mask:0xf bank_mask:0xf
	v_mov_b32_dpp v49, v27 row_ror:15 row_mask:0xf bank_mask:0xf
	v_cmp_gt_i32_e32 vcc, s86, v111
	s_and_saveexec_b64 s[80:81], vcc
	s_cbranch_execz .LBB0_1096
	v_and_b32_e32 v116, 0x1fff, v111
	v_and_b32_e32 v117, 0xff, v111
	v_cmp_gt_i32_e64 s[48:49], s97, v111
	v_cndmask_b32_e64 v112, v91, v112, s[38:39]
	v_mov_b32_e32 v114, v42
	v_cndmask_b32_e64 v113, v117, v116, s[48:49]
	v_cmp_eq_u32_e32 vcc, 0, v113
	s_waitcnt vmcnt(0)
	v_mov_b32_e32 v115, v58
	v_cmp_eq_u32_e64 s[52:53], s78, v116
	v_cndmask_b32_e64 v113, v112, 0, vcc
	v_mov_b32_e32 v112, v70
	v_pk_mul_f32 v[112:113], v[114:115], v[112:113]
	v_cndmask_b32_e64 v109, v89, v109, s[38:39]
	v_add_f32_e32 v42, v112, v113
	v_cndmask_b32_e64 v112, 0, 1, s[52:53]
	v_cmp_eq_u32_e64 s[52:53], s12, v117
	v_cndmask_b32_e64 v110, v110, v90, s[40:41]
	v_mov_b32_e32 v114, v40
	v_cndmask_b32_e64 v113, 0, 1, s[52:53]
	v_cndmask_b32_e64 v112, v113, v112, s[48:49]
	v_and_b32_e32 v112, 1, v112
	v_cmp_eq_u32_e64 s[48:49], 1, v112
	v_cndmask_b32_e64 v113, v109, 0, vcc
	v_mov_b32_e32 v115, v56
	v_mov_b32_e32 v112, v68
	v_cndmask_b32_e64 v110, v110, 0, s[48:49]
	v_pk_mul_f32 v[112:113], v[114:115], v[112:113]
	v_cndmask_b32_e64 v108, v108, v88, s[40:41]
	v_fmac_f32_e32 v42, v62, v110
	v_add_f32_e32 v40, v112, v113
	v_cndmask_b32_e64 v108, v108, 0, s[48:49]
	v_add_f32_e32 v42, v66, v42
	v_fmac_f32_e32 v40, v60, v108
	v_mul_f32_e32 v110, 0x3d372713, v42
	v_add_f32_e32 v40, v64, v40
	v_mul_f32_e32 v110, v42, v110
	v_mul_f32_e32 v108, 0x3d372713, v40
	v_fma_f32 v110, v42, v110, v42
	v_mul_f32_e32 v108, v40, v108
	v_mul_f32_e32 v110, 0xc0135761, v110
	v_fma_f32 v108, v40, v108, v40
	v_exp_f32_e32 v110, v110
	v_mul_f32_e32 v108, 0xc0135761, v108
	v_exp_f32_e32 v108, v108
	v_add_f32_e32 v109, 1.0, v110
	v_rcp_f32_e32 v109, v109
	v_add_f32_e32 v108, 1.0, v108
	v_rcp_f32_e32 v108, v108
	v_mul_f32_e32 v42, v42, v109
	v_mul_f32_e32 v42, v34, v42
	v_mul_f32_e32 v34, v40, v108
	v_cndmask_b32_e64 v40, v75, v107, s[38:39]
	v_cndmask_b32_e64 v109, v40, 0, vcc
	v_mov_b32_e32 v40, v41
	v_mov_b32_e32 v41, v57
	v_mov_b32_e32 v108, v69
	v_pk_mul_f32 v[40:41], v[40:41], v[108:109]
	v_mov_b32_e32 v107, v78
	v_add_f32_e32 v40, v40, v41
	v_cndmask_b32_e64 v41, v106, v74, s[40:41]
	v_cndmask_b32_e64 v41, v41, 0, s[48:49]
	v_fmac_f32_e32 v40, v61, v41
	v_add_f32_e32 v108, v65, v40
	v_mul_f32_e32 v40, 0x3d372713, v108
	v_mul_f32_e32 v40, v108, v40
	v_fma_f32 v40, v108, v40, v108
	v_mul_f32_e32 v40, 0xc0135761, v40
	v_exp_f32_e32 v109, v40
	v_cndmask_b32_e64 v40, v73, v105, s[38:39]
	v_cndmask_b32_e64 v41, v40, 0, vcc
	v_mov_b32_e32 v106, v46
	v_mov_b32_e32 v40, v94
	v_pk_mul_f32 v[40:41], v[106:107], v[40:41]
	v_mov_b32_e32 v46, v47
	v_add_f32_e32 v40, v40, v41
	v_cndmask_b32_e64 v41, v104, v72, s[40:41]
	v_cndmask_b32_e64 v41, v41, 0, s[48:49]
	v_fmac_f32_e32 v40, v82, v41
	v_add_f32_e32 v104, v86, v40
	v_mul_f32_e32 v40, 0x3d372713, v104
	v_mul_f32_e32 v40, v104, v40
	v_fma_f32 v40, v104, v40, v104
	v_mul_f32_e32 v40, 0xc0135761, v40
	v_exp_f32_e32 v40, v40
	v_mov_b32_e32 v47, v79
	v_mul_f32_e32 v34, v32, v34
	v_add_f32_e32 v32, 1.0, v109
	v_add_f32_e32 v40, 1.0, v40
	v_rcp_f32_e32 v105, v40
	v_cndmask_b32_e64 v40, v55, v103, s[38:39]
	v_cndmask_b32_e64 v41, v40, 0, vcc
	v_mov_b32_e32 v40, v95
	v_pk_mul_f32 v[40:41], v[46:47], v[40:41]
	v_rcp_f32_e32 v32, v32
	v_add_f32_e32 v40, v40, v41
	v_cndmask_b32_e64 v41, v102, v54, s[40:41]
	v_cndmask_b32_e64 v41, v41, 0, s[48:49]
	v_fmac_f32_e32 v40, v83, v41
	v_add_f32_e32 v46, v87, v40
	v_mul_f32_e32 v40, 0x3d372713, v46
	v_mul_f32_e32 v40, v46, v40
	v_fma_f32 v40, v46, v40, v46
	v_mul_f32_e32 v40, 0xc0135761, v40
	v_exp_f32_e32 v40, v40
	v_mul_f32_e32 v32, v108, v32
	v_mul_f32_e32 v47, v33, v32
	v_mov_b32_e32 v41, v76
	v_add_f32_e32 v32, 1.0, v40
	v_rcp_f32_e32 v103, v32
	v_cndmask_b32_e64 v32, v53, v101, s[38:39]
	v_cndmask_b32_e64 v33, v32, 0, vcc
	v_mov_b32_e32 v40, v44
	v_mov_b32_e32 v32, v92
	v_pk_mul_f32 v[32:33], v[40:41], v[32:33]
	v_mul_f32_e32 v102, v104, v105
	v_add_f32_e32 v32, v32, v33
	v_cndmask_b32_e64 v33, v100, v52, s[40:41]
	v_cndmask_b32_e64 v33, v33, 0, s[48:49]
	v_fmac_f32_e32 v32, v80, v33
	v_add_f32_e32 v40, v84, v32
	v_mul_f32_e32 v32, 0x3d372713, v40
	v_mul_f32_e32 v32, v40, v32
	v_fma_f32 v32, v40, v32, v40
	v_mul_f32_e32 v32, 0xc0135761, v32
	v_exp_f32_e32 v32, v32
	v_mul_f32_e32 v33, v46, v103
	v_mul_f32_e32 v41, v38, v102
	v_mul_f32_e32 v44, v39, v33
	v_add_f32_e32 v32, 1.0, v32
	v_rcp_f32_e32 v46, v32
	v_cndmask_b32_e64 v32, v50, v98, s[38:39]
	v_cndmask_b32_e64 v33, v32, 0, vcc
	v_mov_b32_e32 v38, v45
	v_mov_b32_e32 v39, v77
	v_mov_b32_e32 v32, v93
	v_pk_mul_f32 v[32:33], v[38:39], v[32:33]
; __device__ __forceinline__ unsigned pk2(float lo, float hi) { const f32x2_cv v = {lo, hi}; const bf16x2_cv b = __builtin_convertvector(v, bf16x2_cv); return __builtin_bit_cast(unsigned, b); }
; __device__ __forceinline__ float dpp_ror1(float v) { return __builtin_bit_cast(float, __builtin_amdgcn_update_dpp(0, __builtin_bit_cast(int, v), 0x121, 0xF, 0xF, false)); }
; __device__ __forceinline__ float dpp_rol1(float v) { return __builtin_bit_cast(float, __builtin_amdgcn_update_dpp(0, __builtin_bit_cast(int, v), 0x12F, 0xF, 0xF, false)); }
;     __device__ __forceinline__ void operator()(const pg8::f32x4 (&acc)[2][2][4][2], const pg8::Unit& u, int wr, int wc, int fr, int fq) const {
;     ...
;             for (int m = 0; m < 4; ++m) {
;                 const int rl = 16 * m + fr, gr = 62 * kb - 1 + rl;
;                 bool first, last; if (gr < ML) { const int t = gr & 8191; first = t == 0; last = t == 8191; } else { const int t = (gr - ML) & 255; first = t == 0; last = t == 255; }
;                 float res[8];
; #pragma unroll
;                 for (int c = 0; c < 8; ++c) {
;                     const int n = c >> 2, e = c & 3;
;                     const float x0 = acc[ai][0][m][n][e];
;                     const float ruC = dpp_ror1(x0), rdN = m < 3 ? dpp_rol1(acc[ai][0][m < 3 ? m + 1 : 3][n][e]) : 0.f;
;                     float xu = fr == 0 ? ruP[c] : ruC, xd = fr == 15 ? rdN : rdC[c];
;                     xu = first ? 0.f : xu; xd = last ? 0.f : xd;
;                     ruP[c] = ruC; rdC[c] = rdN;
;                     const float x = w0[c] * xu + w1[c] * x0 + w2[c] * xd + bb[c];
;                     const float u2 = -2.302208198f * (x + 0.044715f * x * x * x);
;                     res[c] = x * __builtin_amdgcn_rcpf(1.0f + __builtin_amdgcn_exp2f(u2)) * acc[ai][1][m][n][e];
;                 }
;                 if (rl >= 1 && rl <= 62 && gr < nrows) { v4u o; o.x = pk2(res[0], res[1]); o.y = pk2(res[2], res[3]); o.z = pk2(res[4], res[5]); o.w = pk2(res[6], res[7]);
;                     *(v4u*)(G + (size_t)gr * DFF + ch0) = o; }
	v_mov_b32_e32 v38, v43
	v_add_f32_e32 v32, v32, v33
	v_cndmask_b32_e64 v33, v96, v48, s[40:41]
	v_cndmask_b32_e64 v33, v33, 0, s[48:49]
	v_fmac_f32_e32 v32, v81, v33
	v_add_f32_e32 v45, v85, v32
	v_mul_f32_e32 v32, 0x3d372713, v45
	v_mul_f32_e32 v32, v45, v32
	v_fma_f32 v32, v45, v32, v45
	v_mul_f32_e32 v32, 0xc0135761, v32
	v_exp_f32_e32 v96, v32
	v_cndmask_b32_e64 v32, v51, v99, s[38:39]
	v_cndmask_b32_e64 v33, v32, 0, vcc
	v_mov_b32_e32 v39, v59
	v_mov_b32_e32 v32, v71
	v_pk_mul_f32 v[32:33], v[38:39], v[32:33]
	v_add_f32_e32 v39, 1.0, v96
	v_add_f32_e32 v32, v32, v33
	v_cndmask_b32_e64 v33, v97, v49, s[40:41]
	v_cndmask_b32_e64 v33, v33, 0, s[48:49]
	v_fmac_f32_e32 v32, v63, v33
	v_add_f32_e32 v32, v67, v32
	v_mul_f32_e32 v33, 0x3d372713, v32
	v_mul_f32_e32 v33, v32, v33
	v_fma_f32 v33, v32, v33, v32
	v_mul_f32_e32 v33, 0xc0135761, v33
	v_exp_f32_e32 v33, v33
	v_rcp_f32_e32 v39, v39
	v_mul_f32_e32 v38, v40, v46
	v_mul_f32_e32 v36, v36, v38
	v_add_f32_e32 v33, 1.0, v33
	v_rcp_f32_e32 v33, v33
	v_mul_f32_e32 v38, v45, v39
	v_mul_f32_e32 v37, v37, v38
	v_cvt_pk_bf16_f32 v34, v34, v47
	v_mul_f32_e32 v32, v32, v33
	v_mul_f32_e32 v35, v35, v32
	v_cvt_pk_bf16_f32 v32, v36, v37
	v_mov_b64_e32 v[36:37], s[6:7]
	v_mad_i64_i32 v[36:37], s[48:49], v111, s1, v[36:37]
	v_cvt_pk_bf16_f32 v33, v41, v44
	v_cvt_pk_bf16_f32 v35, v42, v35
	v_lshl_add_u64 v[36:37], v[170:171], 1, v[36:37]
	global_store_dwordx4 v[36:37], v[32:35], off sc1
.LBB0_1096:
	s_or_b64 exec, exec, s[80:81]
	v_add_u32_e32 v96, s65, v175
	v_mov_b32_dpp v46, v28 row_ror:1 row_mask:0xf bank_mask:0xf
	v_mov_b32_dpp v44, v12 row_ror:15 row_mask:0xf bank_mask:0xf
	v_mov_b32_dpp v47, v29 row_ror:1 row_mask:0xf bank_mask:0xf
	v_mov_b32_dpp v45, v13 row_ror:15 row_mask:0xf bank_mask:0xf
	v_mov_b32_dpp v42, v30 row_ror:1 row_mask:0xf bank_mask:0xf
	v_mov_b32_dpp v40, v14 row_ror:15 row_mask:0xf bank_mask:0xf
	v_mov_b32_dpp v43, v31 row_ror:1 row_mask:0xf bank_mask:0xf
	v_mov_b32_dpp v41, v15 row_ror:15 row_mask:0xf bank_mask:0xf
	v_mov_b32_dpp v38, v24 row_ror:1 row_mask:0xf bank_mask:0xf
	v_mov_b32_dpp v36, v8 row_ror:15 row_mask:0xf bank_mask:0xf
	v_mov_b32_dpp v39, v25 row_ror:1 row_mask:0xf bank_mask:0xf
	v_mov_b32_dpp v37, v9 row_ror:15 row_mask:0xf bank_mask:0xf
	v_mov_b32_dpp v34, v26 row_ror:1 row_mask:0xf bank_mask:0xf
	v_mov_b32_dpp v32, v10 row_ror:15 row_mask:0xf bank_mask:0xf
	v_mov_b32_dpp v35, v27 row_ror:1 row_mask:0xf bank_mask:0xf
	v_mov_b32_dpp v33, v11 row_ror:15 row_mask:0xf bank_mask:0xf
	v_cmp_gt_i32_e32 vcc, s86, v96
	s_and_saveexec_b64 s[80:81], vcc
	s_cbranch_execz .LBB0_1098
	v_and_b32_e32 v97, 0x1fff, v96
	v_and_b32_e32 v102, 0xff, v96
	v_cmp_gt_i32_e64 s[48:49], s97, v96
	v_cndmask_b32_e64 v91, v34, v91, s[38:39]
	v_cmp_eq_u32_e64 s[52:53], s78, v97
	v_cndmask_b32_e64 v98, v102, v97, s[48:49]
	v_cmp_eq_u32_e32 vcc, 0, v98
	v_mov_b32_e32 v100, v26
	s_waitcnt vmcnt(0)
	v_mov_b32_e32 v101, v58
	v_cndmask_b32_e64 v99, v91, 0, vcc
	v_cndmask_b32_e64 v91, 0, 1, s[52:53]
	v_cmp_eq_u32_e64 s[52:53], s12, v102
	v_mov_b32_e32 v98, v70
	v_pk_mul_f32 v[98:99], v[100:101], v[98:99]
	v_cndmask_b32_e64 v97, 0, 1, s[52:53]
	v_cndmask_b32_e64 v91, v97, v91, s[48:49]
	v_and_b32_e32 v91, 1, v91
	v_cndmask_b32_e64 v90, v90, v32, s[40:41]
	v_cmp_eq_u32_e64 s[48:49], 1, v91
	v_add_f32_e32 v26, v98, v99
	v_cndmask_b32_e64 v89, v38, v89, s[38:39]
	v_cndmask_b32_e64 v90, v90, 0, s[48:49]
	v_fmac_f32_e32 v26, v62, v90
	v_add_f32_e32 v26, v66, v26
	v_mul_f32_e32 v90, 0x3d372713, v26
	v_mul_f32_e32 v90, v26, v90
	v_fma_f32 v90, v26, v90, v26
	v_mul_f32_e32 v90, 0xc0135761, v90
	v_exp_f32_e32 v97, v90
	v_cndmask_b32_e64 v91, v89, 0, vcc
	v_mov_b32_e32 v98, v24
	v_mov_b32_e32 v99, v56
	v_mov_b32_e32 v90, v68
	v_pk_mul_f32 v[90:91], v[98:99], v[90:91]
	v_cndmask_b32_e64 v88, v88, v36, s[40:41]
	v_add_f32_e32 v24, v90, v91
	v_cndmask_b32_e64 v88, v88, 0, s[48:49]
	v_fmac_f32_e32 v24, v60, v88
	v_add_f32_e32 v24, v64, v24
	v_mul_f32_e32 v88, 0x3d372713, v24
	v_mul_f32_e32 v88, v24, v88
	v_fma_f32 v88, v24, v88, v24
	v_mul_f32_e32 v88, 0xc0135761, v88
	v_exp_f32_e32 v88, v88
	v_add_f32_e32 v89, 1.0, v97
	v_rcp_f32_e32 v89, v89
	v_add_f32_e32 v88, 1.0, v88
	v_rcp_f32_e32 v88, v88
	v_mul_f32_e32 v26, v26, v89
	v_mul_f32_e32 v26, v18, v26
	v_mul_f32_e32 v18, v24, v88
	v_cndmask_b32_e64 v24, v39, v75, s[38:39]
	v_cndmask_b32_e64 v89, v24, 0, vcc
	v_mov_b32_e32 v24, v25
	v_mov_b32_e32 v25, v57
	v_mov_b32_e32 v88, v69
	v_pk_mul_f32 v[24:25], v[24:25], v[88:89]
	v_mov_b32_e32 v75, v78
	v_add_f32_e32 v24, v24, v25
	v_cndmask_b32_e64 v25, v74, v37, s[40:41]
	v_cndmask_b32_e64 v25, v25, 0, s[48:49]
	v_fmac_f32_e32 v24, v61, v25
	v_add_f32_e32 v88, v65, v24
	v_mul_f32_e32 v24, 0x3d372713, v88
	v_mul_f32_e32 v24, v88, v24
	v_fma_f32 v24, v88, v24, v88
	v_mul_f32_e32 v24, 0xc0135761, v24
	v_exp_f32_e32 v89, v24
	v_cndmask_b32_e64 v24, v42, v73, s[38:39]
	v_cndmask_b32_e64 v25, v24, 0, vcc
	v_mov_b32_e32 v74, v30
	v_mov_b32_e32 v24, v94
	v_pk_mul_f32 v[24:25], v[74:75], v[24:25]
	v_mov_b32_e32 v30, v31
	v_add_f32_e32 v24, v24, v25
	v_cndmask_b32_e64 v25, v72, v40, s[40:41]
	v_cndmask_b32_e64 v25, v25, 0, s[48:49]
	v_fmac_f32_e32 v24, v82, v25
	v_add_f32_e32 v72, v86, v24
	v_mul_f32_e32 v24, 0x3d372713, v72
	v_mul_f32_e32 v24, v72, v24
	v_fma_f32 v24, v72, v24, v72
	v_mul_f32_e32 v24, 0xc0135761, v24
	v_exp_f32_e32 v24, v24
	v_mov_b32_e32 v31, v79
	v_mul_f32_e32 v18, v16, v18
	v_add_f32_e32 v16, 1.0, v89
	v_add_f32_e32 v24, 1.0, v24
	v_rcp_f32_e32 v73, v24
	v_cndmask_b32_e64 v24, v43, v55, s[38:39]
	v_cndmask_b32_e64 v25, v24, 0, vcc
	v_mov_b32_e32 v24, v95
	v_pk_mul_f32 v[24:25], v[30:31], v[24:25]
; __device__ __forceinline__ unsigned pk2(float lo, float hi) { const f32x2_cv v = {lo, hi}; const bf16x2_cv b = __builtin_convertvector(v, bf16x2_cv); return __builtin_bit_cast(unsigned, b); }
; __device__ __forceinline__ float dpp_ror1(float v) { return __builtin_bit_cast(float, __builtin_amdgcn_update_dpp(0, __builtin_bit_cast(int, v), 0x121, 0xF, 0xF, false)); }
; __device__ __forceinline__ float dpp_rol1(float v) { return __builtin_bit_cast(float, __builtin_amdgcn_update_dpp(0, __builtin_bit_cast(int, v), 0x12F, 0xF, 0xF, false)); }
;     __device__ __forceinline__ void operator()(const pg8::f32x4 (&acc)[2][2][4][2], const pg8::Unit& u, int wr, int wc, int fr, int fq) const {
;     ...
;                 for (int c = 0; c < 8; ++c) {
;                     const int n = c >> 2, e = c & 3;
;                     const float x0 = acc[ai][0][m][n][e];
;                     const float ruC = dpp_ror1(x0), rdN = m < 3 ? dpp_rol1(acc[ai][0][m < 3 ? m + 1 : 3][n][e]) : 0.f;
;                     float xu = fr == 0 ? ruP[c] : ruC, xd = fr == 15 ? rdN : rdC[c];
;                     xu = first ? 0.f : xu; xd = last ? 0.f : xd;
;                     ruP[c] = ruC; rdC[c] = rdN;
;                     const float x = w0[c] * xu + w1[c] * x0 + w2[c] * xd + bb[c];
;                     const float u2 = -2.302208198f * (x + 0.044715f * x * x * x);
;                     res[c] = x * __builtin_amdgcn_rcpf(1.0f + __builtin_amdgcn_exp2f(u2)) * acc[ai][1][m][n][e];
;                 }
;                 if (rl >= 1 && rl <= 62 && gr < nrows) { v4u o; o.x = pk2(res[0], res[1]); o.y = pk2(res[2], res[3]); o.z = pk2(res[4], res[5]); o.w = pk2(res[6], res[7]);
;                     *(v4u*)(G + (size_t)gr * DFF + ch0) = o; }
	v_rcp_f32_e32 v16, v16
	v_add_f32_e32 v24, v24, v25
	v_cndmask_b32_e64 v25, v54, v41, s[40:41]
	v_cndmask_b32_e64 v25, v25, 0, s[48:49]
	v_fmac_f32_e32 v24, v83, v25
	v_add_f32_e32 v30, v87, v24
	v_mul_f32_e32 v24, 0x3d372713, v30
	v_mul_f32_e32 v24, v30, v24
	v_fma_f32 v24, v30, v24, v30
	v_mul_f32_e32 v24, 0xc0135761, v24
	v_exp_f32_e32 v24, v24
	v_mul_f32_e32 v16, v88, v16
	v_mul_f32_e32 v31, v17, v16
	v_mov_b32_e32 v25, v76
	v_add_f32_e32 v16, 1.0, v24
	v_rcp_f32_e32 v55, v16
	v_cndmask_b32_e64 v16, v46, v53, s[38:39]
	v_cndmask_b32_e64 v17, v16, 0, vcc
	v_mov_b32_e32 v24, v28
	v_mov_b32_e32 v16, v92
	v_pk_mul_f32 v[16:17], v[24:25], v[16:17]
	v_mul_f32_e32 v54, v72, v73
	v_add_f32_e32 v16, v16, v17
	v_cndmask_b32_e64 v17, v52, v44, s[40:41]
	v_cndmask_b32_e64 v17, v17, 0, s[48:49]
	v_fmac_f32_e32 v16, v80, v17
	v_add_f32_e32 v24, v84, v16
	v_mul_f32_e32 v16, 0x3d372713, v24
	v_mul_f32_e32 v16, v24, v16
	v_fma_f32 v16, v24, v16, v24
	v_mul_f32_e32 v16, 0xc0135761, v16
	v_exp_f32_e32 v16, v16
	v_mul_f32_e32 v17, v30, v55
	v_mul_f32_e32 v25, v22, v54
	v_mul_f32_e32 v28, v23, v17
	v_add_f32_e32 v16, 1.0, v16
	v_rcp_f32_e32 v30, v16
	v_cndmask_b32_e64 v16, v47, v50, s[38:39]
	v_cndmask_b32_e64 v17, v16, 0, vcc
	v_mov_b32_e32 v22, v29
	v_mov_b32_e32 v23, v77
	v_mov_b32_e32 v16, v93
	v_pk_mul_f32 v[16:17], v[22:23], v[16:17]
	v_mov_b32_e32 v22, v27
	v_add_f32_e32 v16, v16, v17
	v_cndmask_b32_e64 v17, v48, v45, s[40:41]
	v_cndmask_b32_e64 v17, v17, 0, s[48:49]
	v_fmac_f32_e32 v16, v81, v17
	v_add_f32_e32 v29, v85, v16
	v_mul_f32_e32 v16, 0x3d372713, v29
	v_mul_f32_e32 v16, v29, v16
	v_fma_f32 v16, v29, v16, v29
	v_mul_f32_e32 v16, 0xc0135761, v16
	v_exp_f32_e32 v48, v16
	v_cndmask_b32_e64 v16, v35, v51, s[38:39]
	v_cndmask_b32_e64 v17, v16, 0, vcc
	v_mov_b32_e32 v23, v59
	v_mov_b32_e32 v16, v71
	v_pk_mul_f32 v[16:17], v[22:23], v[16:17]
	v_add_f32_e32 v23, 1.0, v48
	v_add_f32_e32 v16, v16, v17
	v_cndmask_b32_e64 v17, v49, v33, s[40:41]
	v_cndmask_b32_e64 v17, v17, 0, s[48:49]
	v_fmac_f32_e32 v16, v63, v17
	v_add_f32_e32 v16, v67, v16
	v_mul_f32_e32 v17, 0x3d372713, v16
	v_mul_f32_e32 v17, v16, v17
	v_fma_f32 v17, v16, v17, v16
	v_mul_f32_e32 v17, 0xc0135761, v17
	v_exp_f32_e32 v17, v17
	v_rcp_f32_e32 v23, v23
	v_mul_f32_e32 v22, v24, v30
	v_mul_f32_e32 v20, v20, v22
	v_add_f32_e32 v17, 1.0, v17
	v_rcp_f32_e32 v17, v17
	v_mul_f32_e32 v22, v29, v23
	v_mul_f32_e32 v21, v21, v22
	v_cvt_pk_bf16_f32 v18, v18, v31
	v_mul_f32_e32 v16, v16, v17
	v_mul_f32_e32 v19, v19, v16
	v_cvt_pk_bf16_f32 v16, v20, v21
	v_mov_b64_e32 v[20:21], s[6:7]
	v_mad_i64_i32 v[20:21], s[48:49], v96, s1, v[20:21]
	v_cvt_pk_bf16_f32 v17, v25, v28
	v_cvt_pk_bf16_f32 v19, v26, v19
	v_lshl_add_u64 v[20:21], v[170:171], 1, v[20:21]
	global_store_dwordx4 v[20:21], v[16:19], off sc1
; __device__ __forceinline__ unsigned pk2(float lo, float hi) { const f32x2_cv v = {lo, hi}; const bf16x2_cv b = __builtin_convertvector(v, bf16x2_cv); return __builtin_bit_cast(unsigned, b); }
; __device__ __forceinline__ float dpp_ror1(float v) { return __builtin_bit_cast(float, __builtin_amdgcn_update_dpp(0, __builtin_bit_cast(int, v), 0x121, 0xF, 0xF, false)); }
; __device__ __forceinline__ float dpp_rol1(float v) { return __builtin_bit_cast(float, __builtin_amdgcn_update_dpp(0, __builtin_bit_cast(int, v), 0x12F, 0xF, 0xF, false)); }
;     __device__ __forceinline__ void operator()(const pg8::f32x4 (&acc)[2][2][4][2], const pg8::Unit& u, int wr, int wc, int fr, int fq) const {
;     ...
;             for (int m = 0; m < 4; ++m) {
;                 const int rl = 16 * m + fr, gr = 62 * kb - 1 + rl;
;                 bool first, last; if (gr < ML) { const int t = gr & 8191; first = t == 0; last = t == 8191; } else { const int t = (gr - ML) & 255; first = t == 0; last = t == 255; }
;                 float res[8];
; #pragma unroll
;                 for (int c = 0; c < 8; ++c) {
;                     const int n = c >> 2, e = c & 3;
;                     const float x0 = acc[ai][0][m][n][e];
;                     const float ruC = dpp_ror1(x0), rdN = m < 3 ? dpp_rol1(acc[ai][0][m < 3 ? m + 1 : 3][n][e]) : 0.f;
;                     float xu = fr == 0 ? ruP[c] : ruC, xd = fr == 15 ? rdN : rdC[c];
;                     xu = first ? 0.f : xu; xd = last ? 0.f : xd;
;                     ruP[c] = ruC; rdC[c] = rdN;
;                     const float x = w0[c] * xu + w1[c] * x0 + w2[c] * xd + bb[c];
;                     const float u2 = -2.302208198f * (x + 0.044715f * x * x * x);
;                     res[c] = x * __builtin_amdgcn_rcpf(1.0f + __builtin_amdgcn_exp2f(u2)) * acc[ai][1][m][n][e];
;                 }
;                 if (rl >= 1 && rl <= 62 && gr < nrows) { v4u o; o.x = pk2(res[0], res[1]); o.y = pk2(res[2], res[3]); o.z = pk2(res[4], res[5]); o.w = pk2(res[6], res[7]);
;                     *(v4u*)(G + (size_t)gr * DFF + ch0) = o; }
.LBB0_1098:
	s_or_b64 exec, exec, s[80:81]
	s_nop 0
	v_add_u32_e32 v16, s65, v176
	v_cmp_gt_i32_e32 vcc, s86, v16
	v_mov_b32_dpp v23, v12 row_ror:1 row_mask:0xf bank_mask:0xf
	v_mov_b32_dpp v24, v13 row_ror:1 row_mask:0xf bank_mask:0xf
	v_mov_b32_dpp v21, v14 row_ror:1 row_mask:0xf bank_mask:0xf
	v_mov_b32_dpp v22, v15 row_ror:1 row_mask:0xf bank_mask:0xf
	v_mov_b32_dpp v19, v8 row_ror:1 row_mask:0xf bank_mask:0xf
	v_mov_b32_dpp v20, v9 row_ror:1 row_mask:0xf bank_mask:0xf
	v_mov_b32_dpp v17, v10 row_ror:1 row_mask:0xf bank_mask:0xf
	v_mov_b32_dpp v18, v11 row_ror:1 row_mask:0xf bank_mask:0xf
	s_and_b64 s[48:49], s[44:45], vcc
	s_and_saveexec_b64 s[52:53], s[48:49]
	s_cbranch_execz .LBB0_1100
	v_and_b32_e32 v25, 0x1fff, v16
	v_and_b32_e32 v26, 0xff, v16
	v_cmp_gt_i32_e32 vcc, s97, v16
	v_cmp_eq_u32_e64 s[48:49], s78, v25
	v_cndmask_b32_e64 v23, v23, v46, s[38:39]
	v_cndmask_b32_e32 v27, v26, v25, vcc
	v_cndmask_b32_e64 v25, 0, 1, s[48:49]
	v_cmp_eq_u32_e64 s[48:49], s12, v26
	v_cndmask_b32_e64 v24, v24, v47, s[38:39]
	s_waitcnt vmcnt(0)
	v_pk_mul_f32 v[12:13], v[12:13], v[92:93]
	v_cndmask_b32_e64 v26, 0, 1, s[48:49]
	v_cndmask_b32_e32 v25, v26, v25, vcc
	v_and_b32_e32 v26, 1, v25
	v_cmp_eq_u32_e64 s[48:49], 0, v27
	v_cmp_eq_u32_e32 vcc, 1, v26
	v_cndmask_b32_e64 v21, v21, v42, s[38:39]
	v_cndmask_b32_e64 v25, v24, 0, s[48:49]
	v_cndmask_b32_e64 v24, v23, 0, s[48:49]
	v_pk_fma_f32 v[12:13], v[76:77], v[24:25], v[12:13]
	v_cndmask_b32_e64 v25, v45, 0, vcc
	v_cndmask_b32_e64 v24, v44, 0, vcc
	v_pk_fma_f32 v[12:13], v[80:81], v[24:25], v[12:13]
	v_cndmask_b32_e64 v22, v22, v43, s[38:39]
	v_pk_add_f32 v[12:13], v[84:85], v[12:13]
	v_pk_mul_f32 v[14:15], v[14:15], v[94:95]
	v_mul_f32_e32 v23, 0x3d372713, v12
	v_mul_f32_e32 v23, v12, v23
	v_fma_f32 v23, v12, v23, v12
	v_mul_f32_e32 v23, 0xc0135761, v23
	v_exp_f32_e32 v23, v23
	v_mul_f32_e32 v24, 0x3d372713, v13
	v_mul_f32_e32 v24, v13, v24
	v_fma_f32 v24, v13, v24, v13
	v_mul_f32_e32 v24, 0xc0135761, v24
	v_add_f32_e32 v23, 1.0, v23
	v_exp_f32_e32 v25, v24
	v_rcp_f32_e32 v24, v23
	v_cndmask_b32_e64 v23, v22, 0, s[48:49]
	v_cndmask_b32_e64 v22, v21, 0, s[48:49]
	v_pk_fma_f32 v[14:15], v[78:79], v[22:23], v[14:15]
	v_cndmask_b32_e64 v23, v41, 0, vcc
	v_cndmask_b32_e64 v22, v40, 0, vcc
	v_pk_fma_f32 v[14:15], v[82:83], v[22:23], v[14:15]
	v_add_f32_e32 v25, 1.0, v25
	v_pk_add_f32 v[14:15], v[86:87], v[14:15]
	v_rcp_f32_e32 v25, v25
	v_mul_f32_e32 v21, 0x3d372713, v14
	v_mul_f32_e32 v21, v14, v21
	v_mul_f32_e32 v22, 0x3d372713, v15
	v_fma_f32 v21, v14, v21, v14
	v_mul_f32_e32 v22, v15, v22
	v_mul_f32_e32 v21, 0xc0135761, v21
	v_fma_f32 v22, v15, v22, v15
	v_exp_f32_e32 v21, v21
	v_mul_f32_e32 v22, 0xc0135761, v22
	v_exp_f32_e32 v23, v22
	v_pk_mul_f32 v[12:13], v[12:13], v[24:25]
	v_add_f32_e32 v21, 1.0, v21
	v_rcp_f32_e32 v22, v21
	v_add_f32_e32 v21, 1.0, v23
	v_rcp_f32_e32 v23, v21
	v_pk_mul_f32 v[4:5], v[4:5], v[12:13]
	v_cndmask_b32_e64 v17, v17, v34, s[38:39]
	v_cndmask_b32_e64 v18, v18, v35, s[38:39]
	v_pk_mul_f32 v[12:13], v[14:15], v[22:23]
	v_cndmask_b32_e64 v14, v19, v38, s[38:39]
	v_cndmask_b32_e64 v15, v20, v39, s[38:39]
	v_pk_mul_f32 v[8:9], v[8:9], v[68:69]
	v_cndmask_b32_e64 v15, v15, 0, s[48:49]
	v_cndmask_b32_e64 v14, v14, 0, s[48:49]
	v_pk_mul_f32 v[10:11], v[10:11], v[70:71]
	v_cndmask_b32_e64 v19, v18, 0, s[48:49]
	v_cndmask_b32_e64 v18, v17, 0, s[48:49]
	v_pk_fma_f32 v[8:9], v[56:57], v[14:15], v[8:9]
	v_cndmask_b32_e64 v15, v37, 0, vcc
	v_cndmask_b32_e64 v14, v36, 0, vcc
	v_pk_fma_f32 v[10:11], v[58:59], v[18:19], v[10:11]
	v_cndmask_b32_e64 v19, v33, 0, vcc
	v_cndmask_b32_e64 v18, v32, 0, vcc
	v_pk_fma_f32 v[8:9], v[60:61], v[14:15], v[8:9]
	v_pk_fma_f32 v[10:11], v[62:63], v[18:19], v[10:11]
	v_pk_add_f32 v[8:9], v[64:65], v[8:9]
	v_pk_add_f32 v[10:11], v[66:67], v[10:11]
	v_mul_f32_e32 v14, 0x3d372713, v8
	v_mul_f32_e32 v15, 0x3d372713, v9
	v_mul_f32_e32 v17, 0x3d372713, v10
	v_mul_f32_e32 v14, v8, v14
	v_mul_f32_e32 v15, v9, v15
	v_mul_f32_e32 v17, v10, v17
	v_mul_f32_e32 v18, 0x3d372713, v11
	v_fma_f32 v14, v8, v14, v8
	v_fma_f32 v15, v9, v15, v9
	v_fma_f32 v17, v10, v17, v10
	v_mul_f32_e32 v18, v11, v18
	v_mul_f32_e32 v14, 0xc0135761, v14
	v_mul_f32_e32 v15, 0xc0135761, v15
	v_mul_f32_e32 v17, 0xc0135761, v17
	v_fma_f32 v18, v11, v18, v11
	v_exp_f32_e32 v14, v14
	v_exp_f32_e32 v15, v15
	v_exp_f32_e32 v17, v17
	v_mul_f32_e32 v18, 0xc0135761, v18
	v_exp_f32_e32 v19, v18
	v_add_f32_e32 v14, 1.0, v14
	v_add_f32_e32 v15, 1.0, v15
	v_add_f32_e32 v17, 1.0, v17
	v_rcp_f32_e32 v14, v14
	v_rcp_f32_e32 v15, v15
	v_rcp_f32_e32 v18, v17
	v_add_f32_e32 v17, 1.0, v19
	v_rcp_f32_e32 v19, v17
	v_pk_mul_f32 v[8:9], v[8:9], v[14:15]
	v_pk_mul_f32 v[6:7], v[6:7], v[12:13]
	v_pk_mul_f32 v[8:9], v[0:1], v[8:9]
	v_pk_mul_f32 v[0:1], v[10:11], v[18:19]
	s_nop 0
	v_pk_mul_f32 v[10:11], v[2:3], v[0:1]
	v_cvt_pk_bf16_f32 v0, v4, v5
	v_mov_b64_e32 v[4:5], s[6:7]
	v_mad_i64_i32 v[4:5], s[48:49], v16, s1, v[4:5]
	v_cvt_pk_bf16_f32 v1, v6, v7
	v_cvt_pk_bf16_f32 v2, v8, v9
	v_cvt_pk_bf16_f32 v3, v10, v11
	v_lshl_add_u64 v[4:5], v[170:171], 1, v[4:5]
	global_store_dwordx4 v[4:5], v[0:3], off sc1

;     __device__ __forceinline__ void operator()(const pg8::f32x4 (&acc)[2][2][4][2], const pg8::Unit& u, int wr, int wc, int fr, int fq) const {
;     ...
;             for (int m = 0; m < 4; ++m) {
;                 const int r = row_off + u.pm * 256 + ai * 128 + wr * 64 + m * 16 + fr;
;                 const bool lat = r < ML; const int bi = lat ? (r >> 13) : 4;
;                 const size_t off = lat ? (size_t)r * 1024 : (size_t)(r - ML) * 1024;
;                 const float* bp = (lat ? base_lat : base_ctx) + off + col0; float* op = (lat ? out_lat : out_ctx) + off + col0;
;                 const float* gp = gate + bi * 6144 + col0;
; #pragma unroll
;                 for (int bj = 0; bj < 2; ++bj)
; #pragma unroll
;                     for (int n = 0; n < 2; ++n) {
;                         const pg8::f32x4 g4 = *(const pg8::f32x4*)(gp + bj * 128 + n * 16), b4 = *(const pg8::f32x4*)(bp + bj * 128 + n * 16);
;                         *(pg8::f32x4*)(op + bj * 128 + n * 16) = b4 + g4 * acc[ai][bj][m][n];
;                     }
.LBB0_1174:
	v_lshl_add_u32 v143, s75, 8, v136
	v_min_i32_e32 v140, 0x8000, v143
	v_readlane_b32 s12, v254, 35
	v_cmp_gt_i32_e32 vcc, s97, v143
	v_ashrrev_i32_e32 v152, 13, v140
	v_ashrrev_i32_e32 v140, 31, v143
	v_add_u32_e32 v141, 0xffff8000, v143
	v_readlane_b32 s13, v254, 36
	v_lshl_or_b32 v134, s74, 8, v138
	v_cndmask_b32_e32 v147, 0, v140, vcc
	v_cndmask_b32_e32 v146, v141, v143, vcc
	v_mov_b32_e32 v142, s66
	v_mov_b32_e32 v140, s13
	v_mov_b32_e32 v144, s65
	v_mov_b32_e32 v141, s12
	v_ashrrev_i32_e32 v135, 31, v134
	v_cndmask_b32_e32 v149, v142, v140, vcc
	v_cndmask_b32_e32 v148, v144, v141, vcc
	v_lshlrev_b64 v[150:151], 12, v[146:147]
	v_lshl_add_u64 v[146:147], v[148:149], 0, v[150:151]
	v_lshlrev_b64 v[134:135], 2, v[134:135]
	v_lshl_add_u64 v[156:157], v[146:147], 0, v[134:135]
	v_mov_b32_e32 v145, s68
	v_mov_b32_e32 v146, s67
	v_cndmask_b32_e32 v149, v145, v140, vcc
	v_cndmask_b32_e32 v148, v146, v141, vcc
	v_lshl_add_u64 v[148:149], v[148:149], 0, v[150:151]
	v_lshl_add_u64 v[158:159], v[148:149], 0, v[134:135]
	v_mul_i32_i24_e32 v148, 0x1800, v152
	v_ashrrev_i32_e32 v149, 31, v148
	v_lshl_add_u64 v[148:149], v[148:149], 2, s[4:5]
	v_lshl_add_u64 v[160:161], v[148:149], 0, v[134:135]
	global_load_dwordx4 v[164:167], v[160:161], off
	global_load_dwordx4 v[168:171], v[156:157], off
	global_load_dwordx4 v[172:175], v[160:161], off offset:64
	global_load_dwordx4 v[176:179], v[156:157], off offset:64
	global_load_dwordx4 v[180:183], v[160:161], off offset:512
	global_load_dwordx4 v[184:187], v[156:157], off offset:512
	global_load_dwordx4 v[188:191], v[160:161], off offset:576
	global_load_dwordx4 v[192:195], v[156:157], off offset:576
	s_mov_b64 s[36:37], -1
	s_waitcnt vmcnt(6) lgkmcnt(0)
	v_pk_fma_f32 v[126:127], v[126:127], v[166:167], v[170:171]
	v_pk_fma_f32 v[124:125], v[124:125], v[164:165], v[168:169]
	global_store_dwordx4 v[158:159], v[124:127], off sc1
	s_waitcnt vmcnt(5) lgkmcnt(0)
	v_pk_fma_f32 v[122:123], v[122:123], v[174:175], v[178:179]
	v_pk_fma_f32 v[120:121], v[120:121], v[172:173], v[176:177]
	global_store_dwordx4 v[158:159], v[120:123], off offset:64 sc1
	s_waitcnt vmcnt(4) lgkmcnt(0)
	v_pk_fma_f32 v[118:119], v[118:119], v[182:183], v[186:187]
	v_pk_fma_f32 v[116:117], v[116:117], v[180:181], v[184:185]
	global_store_dwordx4 v[158:159], v[116:119], off offset:512 sc1
	s_waitcnt vmcnt(3) lgkmcnt(0)
	v_pk_fma_f32 v[114:115], v[114:115], v[190:191], v[194:195]
	v_pk_fma_f32 v[112:113], v[112:113], v[188:189], v[192:193]
	global_store_dwordx4 v[158:159], v[112:115], off offset:576 sc1
	s_nop 1
	v_or_b32_e32 v112, 16, v143
	v_min_i32_e32 v113, 0x8000, v112
	v_cmp_gt_i32_e32 vcc, s97, v112
	v_ashrrev_i32_e32 v116, 13, v113
	v_ashrrev_i32_e32 v113, 31, v112
	v_add_u32_e32 v114, 0xffff8010, v143
	v_cndmask_b32_e32 v113, 0, v113, vcc
	v_cndmask_b32_e32 v112, v114, v112, vcc
	v_cndmask_b32_e32 v115, v142, v140, vcc
	v_cndmask_b32_e32 v114, v144, v141, vcc
	v_lshlrev_b64 v[112:113], 12, v[112:113]
	v_lshl_add_u64 v[114:115], v[114:115], 0, v[112:113]
	v_lshl_add_u64 v[120:121], v[114:115], 0, v[134:135]
	v_cndmask_b32_e32 v115, v145, v140, vcc
	v_cndmask_b32_e32 v114, v146, v141, vcc
	v_lshl_add_u64 v[112:113], v[114:115], 0, v[112:113]
	v_lshl_add_u64 v[122:123], v[112:113], 0, v[134:135]
	v_mul_i32_i24_e32 v112, 0x1800, v116
	v_ashrrev_i32_e32 v113, 31, v112
	v_lshl_add_u64 v[112:113], v[112:113], 2, s[4:5]
	v_lshl_add_u64 v[124:125], v[112:113], 0, v[134:135]
	global_load_dwordx4 v[164:167], v[124:125], off
	global_load_dwordx4 v[168:171], v[120:121], off
	global_load_dwordx4 v[172:175], v[124:125], off offset:64
	global_load_dwordx4 v[176:179], v[120:121], off offset:64
	global_load_dwordx4 v[180:183], v[124:125], off offset:512
	global_load_dwordx4 v[184:187], v[120:121], off offset:512
	global_load_dwordx4 v[188:191], v[124:125], off offset:576
	global_load_dwordx4 v[192:195], v[120:121], off offset:576
	s_waitcnt vmcnt(6) lgkmcnt(0)
	v_pk_fma_f32 v[110:111], v[110:111], v[166:167], v[170:171]
	v_pk_fma_f32 v[108:109], v[108:109], v[164:165], v[168:169]
	global_store_dwordx4 v[122:123], v[108:111], off sc1
	s_waitcnt vmcnt(5) lgkmcnt(0)
	v_pk_fma_f32 v[106:107], v[106:107], v[174:175], v[178:179]
	v_pk_fma_f32 v[104:105], v[104:105], v[172:173], v[176:177]
	global_store_dwordx4 v[122:123], v[104:107], off offset:64 sc1
	s_waitcnt vmcnt(4) lgkmcnt(0)
	v_pk_fma_f32 v[102:103], v[102:103], v[182:183], v[186:187]
	v_pk_fma_f32 v[100:101], v[100:101], v[180:181], v[184:185]
	global_store_dwordx4 v[122:123], v[100:103], off offset:512 sc1
	s_waitcnt vmcnt(3) lgkmcnt(0)
	v_pk_fma_f32 v[98:99], v[98:99], v[190:191], v[194:195]
	v_pk_fma_f32 v[96:97], v[96:97], v[188:189], v[192:193]
	global_store_dwordx4 v[122:123], v[96:99], off offset:576 sc1
	s_nop 1
	v_or_b32_e32 v96, 32, v143
	v_min_i32_e32 v97, 0x8000, v96
	v_cmp_gt_i32_e32 vcc, s97, v96
	v_ashrrev_i32_e32 v100, 13, v97
	v_ashrrev_i32_e32 v97, 31, v96
	v_add_u32_e32 v98, 0xffff8020, v143
	v_cndmask_b32_e32 v97, 0, v97, vcc
	v_cndmask_b32_e32 v96, v98, v96, vcc
	v_cndmask_b32_e32 v99, v142, v140, vcc
	v_cndmask_b32_e32 v98, v144, v141, vcc
	v_lshlrev_b64 v[96:97], 12, v[96:97]
	v_lshl_add_u64 v[98:99], v[98:99], 0, v[96:97]
	v_lshl_add_u64 v[104:105], v[98:99], 0, v[134:135]
	v_cndmask_b32_e32 v99, v145, v140, vcc
	v_cndmask_b32_e32 v98, v146, v141, vcc
	v_lshl_add_u64 v[96:97], v[98:99], 0, v[96:97]
	v_lshl_add_u64 v[106:107], v[96:97], 0, v[134:135]
	v_mul_i32_i24_e32 v96, 0x1800, v100
	v_ashrrev_i32_e32 v97, 31, v96
	v_lshl_add_u64 v[96:97], v[96:97], 2, s[4:5]
	v_lshl_add_u64 v[108:109], v[96:97], 0, v[134:135]
	global_load_dwordx4 v[164:167], v[108:109], off
	global_load_dwordx4 v[168:171], v[104:105], off
	global_load_dwordx4 v[172:175], v[108:109], off offset:64
	global_load_dwordx4 v[176:179], v[104:105], off offset:64
	global_load_dwordx4 v[180:183], v[108:109], off offset:512
	global_load_dwordx4 v[184:187], v[104:105], off offset:512
	global_load_dwordx4 v[188:191], v[108:109], off offset:576
	global_load_dwordx4 v[192:195], v[104:105], off offset:576
	s_waitcnt vmcnt(6) lgkmcnt(0)
;     __device__ __forceinline__ void operator()(const pg8::f32x4 (&acc)[2][2][4][2], const pg8::Unit& u, int wr, int wc, int fr, int fq) const {
;     ...
;             for (int m = 0; m < 4; ++m) {
;                 const int r = row_off + u.pm * 256 + ai * 128 + wr * 64 + m * 16 + fr;
;                 const bool lat = r < ML; const int bi = lat ? (r >> 13) : 4;
;                 const size_t off = lat ? (size_t)r * 1024 : (size_t)(r - ML) * 1024;
;                 const float* bp = (lat ? base_lat : base_ctx) + off + col0; float* op = (lat ? out_lat : out_ctx) + off + col0;
;                 const float* gp = gate + bi * 6144 + col0;
; #pragma unroll
;                 for (int bj = 0; bj < 2; ++bj)
; #pragma unroll
;                     for (int n = 0; n < 2; ++n) {
;                         const pg8::f32x4 g4 = *(const pg8::f32x4*)(gp + bj * 128 + n * 16), b4 = *(const pg8::f32x4*)(bp + bj * 128 + n * 16);
;                         *(pg8::f32x4*)(op + bj * 128 + n * 16) = b4 + g4 * acc[ai][bj][m][n];
;                     }
	v_pk_fma_f32 v[94:95], v[94:95], v[166:167], v[170:171]
	v_pk_fma_f32 v[92:93], v[92:93], v[164:165], v[168:169]
	global_store_dwordx4 v[106:107], v[92:95], off sc1
	s_waitcnt vmcnt(5) lgkmcnt(0)
	v_pk_fma_f32 v[90:91], v[90:91], v[174:175], v[178:179]
	v_pk_fma_f32 v[88:89], v[88:89], v[172:173], v[176:177]
	global_store_dwordx4 v[106:107], v[88:91], off offset:64 sc1
	s_waitcnt vmcnt(4) lgkmcnt(0)
	v_pk_fma_f32 v[86:87], v[86:87], v[182:183], v[186:187]
	v_pk_fma_f32 v[84:85], v[84:85], v[180:181], v[184:185]
	global_store_dwordx4 v[106:107], v[84:87], off offset:512 sc1
	s_waitcnt vmcnt(3) lgkmcnt(0)
	v_pk_fma_f32 v[82:83], v[82:83], v[190:191], v[194:195]
	v_pk_fma_f32 v[80:81], v[80:81], v[188:189], v[192:193]
	global_store_dwordx4 v[106:107], v[80:83], off offset:576 sc1
	s_nop 1
	v_or_b32_e32 v80, 48, v143
	v_min_i32_e32 v81, 0x8000, v80
	v_cmp_gt_i32_e32 vcc, s97, v80
	v_ashrrev_i32_e32 v84, 13, v81
	v_ashrrev_i32_e32 v81, 31, v80
	v_add_u32_e32 v82, 0xffff8030, v143
	v_cndmask_b32_e32 v81, 0, v81, vcc
	v_cndmask_b32_e32 v80, v82, v80, vcc
	v_cndmask_b32_e32 v83, v142, v140, vcc
	v_cndmask_b32_e32 v82, v144, v141, vcc
	v_lshlrev_b64 v[80:81], 12, v[80:81]
	v_lshl_add_u64 v[82:83], v[82:83], 0, v[80:81]
	v_lshl_add_u64 v[88:89], v[82:83], 0, v[134:135]
	v_cndmask_b32_e32 v83, v145, v140, vcc
	v_cndmask_b32_e32 v82, v146, v141, vcc
	v_lshl_add_u64 v[80:81], v[82:83], 0, v[80:81]
	v_lshl_add_u64 v[90:91], v[80:81], 0, v[134:135]
	v_mul_i32_i24_e32 v80, 0x1800, v84
	v_ashrrev_i32_e32 v81, 31, v80
	v_lshl_add_u64 v[80:81], v[80:81], 2, s[4:5]
	v_lshl_add_u64 v[92:93], v[80:81], 0, v[134:135]
	global_load_dwordx4 v[164:167], v[92:93], off
	global_load_dwordx4 v[168:171], v[88:89], off
	global_load_dwordx4 v[172:175], v[92:93], off offset:64
	global_load_dwordx4 v[176:179], v[88:89], off offset:64
	global_load_dwordx4 v[180:183], v[92:93], off offset:512
	global_load_dwordx4 v[184:187], v[88:89], off offset:512
	global_load_dwordx4 v[188:191], v[92:93], off offset:576
	global_load_dwordx4 v[192:195], v[88:89], off offset:576
	s_waitcnt vmcnt(6) lgkmcnt(0)
	v_pk_fma_f32 v[78:79], v[78:79], v[166:167], v[170:171]
	v_pk_fma_f32 v[76:77], v[76:77], v[164:165], v[168:169]
	global_store_dwordx4 v[90:91], v[76:79], off sc1
	s_waitcnt vmcnt(5) lgkmcnt(0)
	v_pk_fma_f32 v[74:75], v[74:75], v[174:175], v[178:179]
	v_pk_fma_f32 v[72:73], v[72:73], v[172:173], v[176:177]
	global_store_dwordx4 v[90:91], v[72:75], off offset:64 sc1
	s_waitcnt vmcnt(4) lgkmcnt(0)
	v_pk_fma_f32 v[70:71], v[70:71], v[182:183], v[186:187]
	v_pk_fma_f32 v[68:69], v[68:69], v[180:181], v[184:185]
	global_store_dwordx4 v[90:91], v[68:71], off offset:512 sc1
	s_waitcnt vmcnt(3) lgkmcnt(0)
	v_pk_fma_f32 v[66:67], v[66:67], v[190:191], v[194:195]
	v_pk_fma_f32 v[64:65], v[64:65], v[188:189], v[192:193]
	global_store_dwordx4 v[90:91], v[64:67], off offset:576 sc1
	s_nop 1
	v_add_u32_e32 v64, 0x80, v143
	v_min_i32_e32 v65, 0x8000, v64
	v_cmp_gt_i32_e32 vcc, s97, v64
	v_ashrrev_i32_e32 v68, 13, v65
	v_ashrrev_i32_e32 v65, 31, v64
	v_add_u32_e32 v66, 0xffff8080, v143
	v_cndmask_b32_e32 v65, 0, v65, vcc
	v_cndmask_b32_e32 v64, v66, v64, vcc
	v_cndmask_b32_e32 v67, v142, v140, vcc
	v_cndmask_b32_e32 v66, v144, v141, vcc
	v_lshlrev_b64 v[64:65], 12, v[64:65]
	v_lshl_add_u64 v[66:67], v[66:67], 0, v[64:65]
	v_lshl_add_u64 v[72:73], v[66:67], 0, v[134:135]
	v_cndmask_b32_e32 v67, v145, v140, vcc
	v_cndmask_b32_e32 v66, v146, v141, vcc
	v_lshl_add_u64 v[64:65], v[66:67], 0, v[64:65]
	v_lshl_add_u64 v[74:75], v[64:65], 0, v[134:135]
	v_mul_i32_i24_e32 v64, 0x1800, v68
	v_ashrrev_i32_e32 v65, 31, v64
	v_lshl_add_u64 v[64:65], v[64:65], 2, s[4:5]
	v_lshl_add_u64 v[76:77], v[64:65], 0, v[134:135]
	global_load_dwordx4 v[164:167], v[76:77], off
	global_load_dwordx4 v[168:171], v[72:73], off
	global_load_dwordx4 v[172:175], v[76:77], off offset:64
	global_load_dwordx4 v[176:179], v[72:73], off offset:64
	global_load_dwordx4 v[180:183], v[76:77], off offset:512
	global_load_dwordx4 v[184:187], v[72:73], off offset:512
	global_load_dwordx4 v[188:191], v[76:77], off offset:576
	global_load_dwordx4 v[192:195], v[72:73], off offset:576
	s_waitcnt vmcnt(6) lgkmcnt(0)
	v_pk_fma_f32 v[62:63], v[62:63], v[166:167], v[170:171]
	v_pk_fma_f32 v[60:61], v[60:61], v[164:165], v[168:169]
	global_store_dwordx4 v[74:75], v[60:63], off sc1
	s_waitcnt vmcnt(5) lgkmcnt(0)
	v_pk_fma_f32 v[58:59], v[58:59], v[174:175], v[178:179]
	v_pk_fma_f32 v[56:57], v[56:57], v[172:173], v[176:177]
	global_store_dwordx4 v[74:75], v[56:59], off offset:64 sc1
	s_waitcnt vmcnt(4) lgkmcnt(0)
	v_pk_fma_f32 v[54:55], v[54:55], v[182:183], v[186:187]
	v_pk_fma_f32 v[52:53], v[52:53], v[180:181], v[184:185]
	global_store_dwordx4 v[74:75], v[52:55], off offset:512 sc1
	s_waitcnt vmcnt(3) lgkmcnt(0)
	v_pk_fma_f32 v[50:51], v[50:51], v[190:191], v[194:195]
	v_pk_fma_f32 v[48:49], v[48:49], v[188:189], v[192:193]
	global_store_dwordx4 v[74:75], v[48:51], off offset:576 sc1
	s_nop 1
	v_add_u32_e32 v48, 0x90, v143
	v_min_i32_e32 v49, 0x8000, v48
	v_cmp_gt_i32_e32 vcc, s97, v48
	v_ashrrev_i32_e32 v52, 13, v49
	v_ashrrev_i32_e32 v49, 31, v48
	v_add_u32_e32 v50, 0xffff8090, v143
	v_cndmask_b32_e32 v49, 0, v49, vcc
	v_cndmask_b32_e32 v48, v50, v48, vcc
	v_cndmask_b32_e32 v51, v142, v140, vcc
	v_cndmask_b32_e32 v50, v144, v141, vcc
	v_lshlrev_b64 v[48:49], 12, v[48:49]
	v_lshl_add_u64 v[50:51], v[50:51], 0, v[48:49]
	v_lshl_add_u64 v[56:57], v[50:51], 0, v[134:135]
	v_cndmask_b32_e32 v51, v145, v140, vcc
	v_cndmask_b32_e32 v50, v146, v141, vcc
	v_lshl_add_u64 v[48:49], v[50:51], 0, v[48:49]
	v_lshl_add_u64 v[58:59], v[48:49], 0, v[134:135]
	v_mul_i32_i24_e32 v48, 0x1800, v52
	v_ashrrev_i32_e32 v49, 31, v48
	v_lshl_add_u64 v[48:49], v[48:49], 2, s[4:5]
	v_lshl_add_u64 v[60:61], v[48:49], 0, v[134:135]
	global_load_dwordx4 v[164:167], v[60:61], off
	global_load_dwordx4 v[168:171], v[56:57], off
	global_load_dwordx4 v[172:175], v[60:61], off offset:64
	global_load_dwordx4 v[176:179], v[56:57], off offset:64
	global_load_dwordx4 v[180:183], v[60:61], off offset:512
	global_load_dwordx4 v[184:187], v[56:57], off offset:512
	global_load_dwordx4 v[188:191], v[60:61], off offset:576
	global_load_dwordx4 v[192:195], v[56:57], off offset:576
	s_waitcnt vmcnt(6) lgkmcnt(0)
;     __device__ __forceinline__ void operator()(const pg8::f32x4 (&acc)[2][2][4][2], const pg8::Unit& u, int wr, int wc, int fr, int fq) const {
;     ...
;             for (int m = 0; m < 4; ++m) {
;                 const int r = row_off + u.pm * 256 + ai * 128 + wr * 64 + m * 16 + fr;
;                 const bool lat = r < ML; const int bi = lat ? (r >> 13) : 4;
;                 const size_t off = lat ? (size_t)r * 1024 : (size_t)(r - ML) * 1024;
;                 const float* bp = (lat ? base_lat : base_ctx) + off + col0; float* op = (lat ? out_lat : out_ctx) + off + col0;
;                 const float* gp = gate + bi * 6144 + col0;
; #pragma unroll
;                 for (int bj = 0; bj < 2; ++bj)
; #pragma unroll
;                     for (int n = 0; n < 2; ++n) {
;                         const pg8::f32x4 g4 = *(const pg8::f32x4*)(gp + bj * 128 + n * 16), b4 = *(const pg8::f32x4*)(bp + bj * 128 + n * 16);
;                         *(pg8::f32x4*)(op + bj * 128 + n * 16) = b4 + g4 * acc[ai][bj][m][n];
;                     }
	v_pk_fma_f32 v[46:47], v[46:47], v[166:167], v[170:171]
	v_pk_fma_f32 v[44:45], v[44:45], v[164:165], v[168:169]
	global_store_dwordx4 v[58:59], v[44:47], off sc1
	s_waitcnt vmcnt(5) lgkmcnt(0)
	v_pk_fma_f32 v[42:43], v[42:43], v[174:175], v[178:179]
	v_pk_fma_f32 v[40:41], v[40:41], v[172:173], v[176:177]
	global_store_dwordx4 v[58:59], v[40:43], off offset:64 sc1
	s_waitcnt vmcnt(4) lgkmcnt(0)
	v_pk_fma_f32 v[38:39], v[38:39], v[182:183], v[186:187]
	v_pk_fma_f32 v[36:37], v[36:37], v[180:181], v[184:185]
	global_store_dwordx4 v[58:59], v[36:39], off offset:512 sc1
	s_waitcnt vmcnt(3) lgkmcnt(0)
	v_pk_fma_f32 v[34:35], v[34:35], v[190:191], v[194:195]
	v_pk_fma_f32 v[32:33], v[32:33], v[188:189], v[192:193]
	global_store_dwordx4 v[58:59], v[32:35], off offset:576 sc1
	s_nop 1
	v_add_u32_e32 v32, 0xa0, v143
	v_min_i32_e32 v33, 0x8000, v32
	v_cmp_gt_i32_e32 vcc, s97, v32
	v_ashrrev_i32_e32 v36, 13, v33
	v_ashrrev_i32_e32 v33, 31, v32
	v_add_u32_e32 v34, 0xffff80a0, v143
	v_cndmask_b32_e32 v33, 0, v33, vcc
	v_cndmask_b32_e32 v32, v34, v32, vcc
	v_cndmask_b32_e32 v35, v142, v140, vcc
	v_cndmask_b32_e32 v34, v144, v141, vcc
	v_lshlrev_b64 v[32:33], 12, v[32:33]
	v_lshl_add_u64 v[34:35], v[34:35], 0, v[32:33]
	v_lshl_add_u64 v[40:41], v[34:35], 0, v[134:135]
	v_cndmask_b32_e32 v35, v145, v140, vcc
	v_cndmask_b32_e32 v34, v146, v141, vcc
	v_lshl_add_u64 v[32:33], v[34:35], 0, v[32:33]
	v_lshl_add_u64 v[42:43], v[32:33], 0, v[134:135]
	v_mul_i32_i24_e32 v32, 0x1800, v36
	v_ashrrev_i32_e32 v33, 31, v32
	v_lshl_add_u64 v[32:33], v[32:33], 2, s[4:5]
	v_lshl_add_u64 v[44:45], v[32:33], 0, v[134:135]
	global_load_dwordx4 v[164:167], v[44:45], off
	global_load_dwordx4 v[168:171], v[40:41], off
	global_load_dwordx4 v[172:175], v[44:45], off offset:64
	global_load_dwordx4 v[176:179], v[40:41], off offset:64
	global_load_dwordx4 v[180:183], v[44:45], off offset:512
	global_load_dwordx4 v[184:187], v[40:41], off offset:512
	global_load_dwordx4 v[188:191], v[44:45], off offset:576
	global_load_dwordx4 v[192:195], v[40:41], off offset:576
	s_waitcnt vmcnt(6) lgkmcnt(0)
	v_pk_fma_f32 v[30:31], v[30:31], v[166:167], v[170:171]
	v_pk_fma_f32 v[28:29], v[28:29], v[164:165], v[168:169]
	global_store_dwordx4 v[42:43], v[28:31], off sc1
	s_waitcnt vmcnt(5) lgkmcnt(0)
	v_pk_fma_f32 v[26:27], v[26:27], v[174:175], v[178:179]
	v_pk_fma_f32 v[24:25], v[24:25], v[172:173], v[176:177]
	global_store_dwordx4 v[42:43], v[24:27], off offset:64 sc1
	s_waitcnt vmcnt(4) lgkmcnt(0)
	v_pk_fma_f32 v[22:23], v[22:23], v[182:183], v[186:187]
	v_pk_fma_f32 v[20:21], v[20:21], v[180:181], v[184:185]
	global_store_dwordx4 v[42:43], v[20:23], off offset:512 sc1
	s_waitcnt vmcnt(3) lgkmcnt(0)
	v_pk_fma_f32 v[18:19], v[18:19], v[190:191], v[194:195]
	v_pk_fma_f32 v[16:17], v[16:17], v[188:189], v[192:193]
	global_store_dwordx4 v[42:43], v[16:19], off offset:576 sc1
	s_nop 1
	v_add_u32_e32 v16, 0xb0, v143
	v_min_i32_e32 v17, 0x8000, v16
	v_cmp_gt_i32_e32 vcc, s97, v16
	v_ashrrev_i32_e32 v20, 13, v17
	v_ashrrev_i32_e32 v17, 31, v16
	v_add_u32_e32 v18, 0xffff80b0, v143
	v_cndmask_b32_e32 v17, 0, v17, vcc
	v_cndmask_b32_e32 v16, v18, v16, vcc
	v_cndmask_b32_e32 v19, v142, v140, vcc
	v_cndmask_b32_e32 v18, v144, v141, vcc
	v_lshlrev_b64 v[16:17], 12, v[16:17]
	v_lshl_add_u64 v[18:19], v[18:19], 0, v[16:17]
	v_lshl_add_u64 v[24:25], v[18:19], 0, v[134:135]
	v_cndmask_b32_e32 v19, v145, v140, vcc
	v_cndmask_b32_e32 v18, v146, v141, vcc
	v_lshl_add_u64 v[16:17], v[18:19], 0, v[16:17]
	v_lshl_add_u64 v[26:27], v[16:17], 0, v[134:135]
	v_mul_i32_i24_e32 v16, 0x1800, v20
	v_ashrrev_i32_e32 v17, 31, v16
	v_lshl_add_u64 v[16:17], v[16:17], 2, s[4:5]
	v_lshl_add_u64 v[28:29], v[16:17], 0, v[134:135]
	global_load_dwordx4 v[164:167], v[28:29], off
	global_load_dwordx4 v[168:171], v[24:25], off
	global_load_dwordx4 v[172:175], v[28:29], off offset:64
	global_load_dwordx4 v[176:179], v[24:25], off offset:64
	global_load_dwordx4 v[180:183], v[28:29], off offset:512
	global_load_dwordx4 v[184:187], v[24:25], off offset:512
	global_load_dwordx4 v[188:191], v[28:29], off offset:576
	global_load_dwordx4 v[192:195], v[24:25], off offset:576
	s_and_b64 vcc, exec, s[38:39]
	s_waitcnt vmcnt(6) lgkmcnt(0)
	v_pk_fma_f32 v[14:15], v[14:15], v[166:167], v[170:171]
	v_pk_fma_f32 v[12:13], v[12:13], v[164:165], v[168:169]
	global_store_dwordx4 v[26:27], v[12:15], off sc1
	s_waitcnt vmcnt(5) lgkmcnt(0)
	v_pk_fma_f32 v[10:11], v[10:11], v[174:175], v[178:179]
	v_pk_fma_f32 v[8:9], v[8:9], v[172:173], v[176:177]
	global_store_dwordx4 v[26:27], v[8:11], off offset:64 sc1
	s_waitcnt vmcnt(4) lgkmcnt(0)
	v_pk_fma_f32 v[6:7], v[6:7], v[182:183], v[186:187]
	v_pk_fma_f32 v[4:5], v[4:5], v[180:181], v[184:185]
	global_store_dwordx4 v[26:27], v[4:7], off offset:512 sc1
	s_waitcnt vmcnt(3) lgkmcnt(0)
	v_pk_fma_f32 v[2:3], v[2:3], v[190:191], v[194:195]
	v_pk_fma_f32 v[0:1], v[0:1], v[188:189], v[192:193]
	global_store_dwordx4 v[26:27], v[0:3], off offset:576 sc1
	s_cbranch_vccnz .LBB0_1163
	s_andn2_b64 vcc, exec, s[2:3]
	s_cbranch_vccnz .LBB0_1162
	s_barrier
	s_branch .LBB0_1162
